# K-loop LDS-DMA staging rebalanced 2/6 -> 3/5 pieces per load segment (one As piece staged one segment later; SP2 waits vmcnt(7))
# speedup vs baseline: 1.0077x; 1.0052x over previous
; #define PG8_STAGE(bufoff, gbase, voff) do { const int so_ = (int)(unsigned)((const char*)(gbase) - base_##voff); _Pragma("unroll") for (int _i = 0; _i < 2; ++_i) \
;         __builtin_amdgcn_raw_ptr_buffer_load_lds(rs_##voff, (PG8_LAS unsigned*)(lds + (bufoff) + ldsw + _i * 8192), 16, (int)(voff)[_i], so_, 0, 0); } while (0)
; #define PG8_LDA(dst, b, h) do { _Pragma("unroll") for (int m = 0; m < 4; ++m) _Pragma("unroll") for (int k = 0; k < 2; ++k) dst[m][k] = *(const PG8_LAS bf16x8*)(lds + PG8_SA(b, h) + aoff + m * 2048 + k * 1024); } while (0)
; #define PG8_LDB(dst, b, h) do { _Pragma("unroll") for (int n = 0; n < 2; ++n) _Pragma("unroll") for (int k = 0; k < 2; ++k) dst[n][k] = *(const PG8_LAS bf16x8*)(lds + PG8_SB(b, h) + boff + n * 2048 + k * 1024); } while (0)
; #define PG8_MMA(ai, bj, At, Bt) do { __builtin_amdgcn_s_setprio(1); _Pragma("unroll") for (int m = 0; m < 4; ++m) _Pragma("unroll") for (int n = 0; n < 2; ++n) _Pragma("unroll") for (int k = 0; k < 2; ++k) \
;         acc[ai][bj][m][n] = __builtin_amdgcn_mfma_f32_16x16x32_bf16(Bt[n][k], At[m][k], acc[ai][bj][m][n], 0, 0, 0); __builtin_amdgcn_s_setprio(0); } while (0)
; template <class Epi, class Sched, bool ALIGN_EPI = false, bool SP2 = false>
; __device__ __forceinline__ void gemm_phase(PG8_LAS unsigned char* lds, const Gemm g, const Sched& S, const Epi& E, int tid_in) {
;     ...
;             PG8_LDB(B0, 0, 0); PG8_LDB(B1, 0, 1); PG8_SCHED; PG8_LDA(At, 0, 0); PG8_STAGE(PG8_SA(1, 1), a1 + hstepA, voffA);
;             PG8_WAIT_V(8); PG8_WAIT_L(0); PG8_BAR; PG8_MMA(0, 0, At, B0); PG8_MMA(0, 1, At, B1); PG8_BAR; PG8_SCHED;
;             PG8_LDA(At, 0, 1); PG8_STAGE(PG8_SB(0, 0), b2, voffB); PG8_STAGE(PG8_SB(0, 1), b2 + hstepB, voffB); PG8_STAGE(PG8_SA(0, 0), a2, voffA);
;             PG8_WAIT_V(8); PG8_WAIT_L(0); PG8_BAR; PG8_MMA(1, 0, At, B0); PG8_MMA(1, 1, At, B1); PG8_BAR; PG8_SCHED;
;             PG8_LDB(B0, 1, 0); PG8_LDB(B1, 1, 1); PG8_SCHED; PG8_LDA(At, 1, 0); PG8_STAGE(PG8_SA(0, 1), a2 + hstepA, voffA);
;             PG8_WAIT_V(8); PG8_WAIT_L(0); PG8_BAR; PG8_MMA(0, 0, At, B0); PG8_MMA(0, 1, At, B1); PG8_BAR; PG8_SCHED;
;             PG8_LDA(At, 1, 1); PG8_STAGE(PG8_SB(1, 0), b3, voffB); PG8_STAGE(PG8_SB(1, 1), b3 + hstepB, voffB); PG8_STAGE(PG8_SA(1, 0), a3, voffA);
;             PG8_WAIT_V(8); PG8_WAIT_L(0); PG8_BAR; PG8_MMA(1, 0, At, B0); PG8_MMA(1, 1, At, B1); PG8_BAR; PG8_SCHED;
.LBB0_312:
	v_add_u32_e32 v0, 0x10000, v237
	ds_read_b128 v[130:133], v0
	ds_read_b128 v[134:137], v0 offset:1024
	ds_read_b128 v[138:141], v0 offset:2048
	ds_read_b128 v[142:145], v0 offset:3072
	v_add_u32_e32 v0, 0x14000, v237
	ds_read_b128 v[146:149], v0
	ds_read_b128 v[150:153], v0 offset:1024
	ds_read_b128 v[154:157], v0 offset:2048
	ds_read_b128 v[158:161], v0 offset:3072
	s_add_u32 s16, s12, 0x100
	s_addc_u32 s17, s13, 0
	s_sub_i32 s12, s12, s4
	s_add_i32 s12, s12, 0x80080
	s_sub_i32 s36, s12, 0x80000
	s_cmp_eq_u32 s23, 28
	s_cselect_b32 s13, s19, s16
	s_mov_b32 m0, s69
	ds_read_b128 v[162:165], v238
	ds_read_b128 v[166:169], v238 offset:1024
	ds_read_b128 v[170:173], v238 offset:2048
	ds_read_b128 v[174:177], v238 offset:3072
	ds_read_b128 v[178:181], v238 offset:4096
	ds_read_b128 v[182:185], v238 offset:5120
	ds_read_b128 v[186:189], v238 offset:6144
	ds_read_b128 v[190:193], v238 offset:7168
	s_mov_b32 m0, s78
	s_nop 0
	buffer_load_dwordx4 v211, s[4:7], s36 offen lds
	s_mov_b32 m0, s69
	s_nop 0
	buffer_load_dwordx4 v195, s[4:7], s12 offen lds
	s_mov_b32 m0, s67
	s_nop 0
	buffer_load_dwordx4 v211, s[4:7], s12 offen lds
	s_waitcnt vmcnt(8)
	s_waitcnt lgkmcnt(0)
	s_barrier
	s_setprio 1
	s_waitcnt lgkmcnt(0)
	v_mfma_f32_16x16x32_bf16 v[126:129], v[130:133], v[162:165], v[126:129]
	v_mfma_f32_16x16x32_bf16 v[122:125], v[138:141], v[162:165], v[122:125]
	v_mfma_f32_16x16x32_bf16 v[110:113], v[130:133], v[170:173], v[110:113]
	v_mfma_f32_16x16x32_bf16 v[106:109], v[138:141], v[170:173], v[106:109]
	v_mfma_f32_16x16x32_bf16 v[94:97], v[130:133], v[178:181], v[94:97]
	v_mfma_f32_16x16x32_bf16 v[90:93], v[138:141], v[178:181], v[90:93]
	v_mfma_f32_16x16x32_bf16 v[78:81], v[130:133], v[186:189], v[78:81]
	v_mfma_f32_16x16x32_bf16 v[74:77], v[138:141], v[186:189], v[74:77]
	v_mfma_f32_16x16x32_bf16 v[126:129], v[134:137], v[166:169], v[126:129]
	v_mfma_f32_16x16x32_bf16 v[122:125], v[142:145], v[166:169], v[122:125]
	v_mfma_f32_16x16x32_bf16 v[110:113], v[134:137], v[174:177], v[110:113]
	v_mfma_f32_16x16x32_bf16 v[106:109], v[142:145], v[174:177], v[106:109]
	v_mfma_f32_16x16x32_bf16 v[94:97], v[134:137], v[182:185], v[94:97]
	v_mfma_f32_16x16x32_bf16 v[90:93], v[142:145], v[182:185], v[90:93]
	v_mfma_f32_16x16x32_bf16 v[78:81], v[134:137], v[190:193], v[78:81]
	v_mfma_f32_16x16x32_bf16 v[74:77], v[142:145], v[190:193], v[74:77]
	s_setprio 0
	s_setprio 1
	v_mfma_f32_16x16x32_bf16 v[118:121], v[146:149], v[162:165], v[118:121]
	v_mfma_f32_16x16x32_bf16 v[114:117], v[154:157], v[162:165], v[114:117]
	v_mfma_f32_16x16x32_bf16 v[102:105], v[146:149], v[170:173], v[102:105]
	v_mfma_f32_16x16x32_bf16 v[98:101], v[154:157], v[170:173], v[98:101]
	v_mfma_f32_16x16x32_bf16 v[86:89], v[146:149], v[178:181], v[86:89]
	v_mfma_f32_16x16x32_bf16 v[82:85], v[154:157], v[178:181], v[82:85]
	v_mfma_f32_16x16x32_bf16 v[70:73], v[146:149], v[186:189], v[70:73]
	v_mfma_f32_16x16x32_bf16 v[66:69], v[154:157], v[186:189], v[66:69]
	v_mfma_f32_16x16x32_bf16 v[118:121], v[150:153], v[166:169], v[118:121]
	v_mfma_f32_16x16x32_bf16 v[114:117], v[158:161], v[166:169], v[114:117]
	v_mfma_f32_16x16x32_bf16 v[102:105], v[150:153], v[174:177], v[102:105]
	v_mfma_f32_16x16x32_bf16 v[98:101], v[158:161], v[174:177], v[98:101]
	v_mfma_f32_16x16x32_bf16 v[86:89], v[150:153], v[182:185], v[86:89]
	v_mfma_f32_16x16x32_bf16 v[82:85], v[158:161], v[182:185], v[82:85]
	v_mfma_f32_16x16x32_bf16 v[70:73], v[150:153], v[190:193], v[70:73]
	v_mfma_f32_16x16x32_bf16 v[66:69], v[158:161], v[190:193], v[66:69]
	s_setprio 0
	s_barrier
	s_cselect_b32 s12, s15, s20
	s_mov_b32 m0, s61
	s_mov_b32 s42, s6
	s_mov_b32 s43, s7
	s_sub_i32 s12, s12, s40
	ds_read_b128 v[162:165], v238 offset:16384
	ds_read_b128 v[166:169], v238 offset:17408
	ds_read_b128 v[170:173], v238 offset:18432
	ds_read_b128 v[174:177], v238 offset:19456
	ds_read_b128 v[178:181], v238 offset:20480
	ds_read_b128 v[182:185], v238 offset:21504
	ds_read_b128 v[186:189], v238 offset:22528
	ds_read_b128 v[190:193], v238 offset:23552
	buffer_load_dwordx4 v207, s[40:43], s12 offen lds
	s_mov_b32 m0, s62
	s_add_i32 s36, s12, 0x80000
	buffer_load_dwordx4 v224, s[40:43], s12 offen lds
	s_mov_b32 m0, s63
	s_sub_i32 s13, s13, s4
	buffer_load_dwordx4 v207, s[40:43], s36 offen lds
	s_mov_b32 m0, s71
	s_nop 0
	buffer_load_dwordx4 v224, s[40:43], s36 offen lds
	s_mov_b32 m0, s53
	s_nop 0
	buffer_load_dwordx4 v195, s[4:7], s13 offen lds
	s_waitcnt vmcnt(7)
	s_waitcnt lgkmcnt(0)
	s_barrier
	s_setprio 1
	s_waitcnt lgkmcnt(0)
	v_mfma_f32_16x16x32_bf16 v[62:65], v[130:133], v[162:165], v[62:65]
	v_mfma_f32_16x16x32_bf16 v[58:61], v[138:141], v[162:165], v[58:61]
	v_mfma_f32_16x16x32_bf16 v[46:49], v[130:133], v[170:173], v[46:49]
	v_mfma_f32_16x16x32_bf16 v[42:45], v[138:141], v[170:173], v[42:45]
	v_mfma_f32_16x16x32_bf16 v[30:33], v[130:133], v[178:181], v[30:33]
	v_mfma_f32_16x16x32_bf16 v[26:29], v[138:141], v[178:181], v[26:29]
	v_mfma_f32_16x16x32_bf16 v[14:17], v[130:133], v[186:189], v[14:17]
	v_mfma_f32_16x16x32_bf16 v[10:13], v[138:141], v[186:189], v[10:13]
	v_mfma_f32_16x16x32_bf16 v[62:65], v[134:137], v[166:169], v[62:65]
	v_mfma_f32_16x16x32_bf16 v[58:61], v[142:145], v[166:169], v[58:61]
	v_mfma_f32_16x16x32_bf16 v[46:49], v[134:137], v[174:177], v[46:49]
	v_mfma_f32_16x16x32_bf16 v[42:45], v[142:145], v[174:177], v[42:45]
	v_mfma_f32_16x16x32_bf16 v[30:33], v[134:137], v[182:185], v[30:33]
	v_mfma_f32_16x16x32_bf16 v[26:29], v[142:145], v[182:185], v[26:29]
	v_mfma_f32_16x16x32_bf16 v[14:17], v[134:137], v[190:193], v[14:17]
	v_mfma_f32_16x16x32_bf16 v[10:13], v[142:145], v[190:193], v[10:13]
	s_setprio 0
	s_setprio 1
	v_mfma_f32_16x16x32_bf16 v[54:57], v[146:149], v[162:165], v[54:57]
	v_mfma_f32_16x16x32_bf16 v[50:53], v[154:157], v[162:165], v[50:53]
	v_mfma_f32_16x16x32_bf16 v[38:41], v[146:149], v[170:173], v[38:41]
	v_mfma_f32_16x16x32_bf16 v[34:37], v[154:157], v[170:173], v[34:37]
	v_mfma_f32_16x16x32_bf16 v[22:25], v[146:149], v[178:181], v[22:25]
	v_mfma_f32_16x16x32_bf16 v[18:21], v[154:157], v[178:181], v[18:21]
	v_mfma_f32_16x16x32_bf16 v[6:9], v[146:149], v[186:189], v[6:9]
	v_mfma_f32_16x16x32_bf16 v[2:5], v[154:157], v[186:189], v[2:5]
	v_mfma_f32_16x16x32_bf16 v[54:57], v[150:153], v[166:169], v[54:57]
	v_mfma_f32_16x16x32_bf16 v[50:53], v[158:161], v[166:169], v[50:53]
	v_mfma_f32_16x16x32_bf16 v[38:41], v[150:153], v[174:177], v[38:41]
	v_mfma_f32_16x16x32_bf16 v[34:37], v[158:161], v[174:177], v[34:37]
	v_mfma_f32_16x16x32_bf16 v[22:25], v[150:153], v[182:185], v[22:25]
	v_mfma_f32_16x16x32_bf16 v[18:21], v[158:161], v[182:185], v[18:21]
	v_mfma_f32_16x16x32_bf16 v[6:9], v[150:153], v[190:193], v[6:9]
	v_mfma_f32_16x16x32_bf16 v[2:5], v[158:161], v[190:193], v[2:5]
	s_setprio 0
	s_barrier
; #define PG8_STAGE(bufoff, gbase, voff) do { const int so_ = (int)(unsigned)((const char*)(gbase) - base_##voff); _Pragma("unroll") for (int _i = 0; _i < 2; ++_i) \
;         __builtin_amdgcn_raw_ptr_buffer_load_lds(rs_##voff, (PG8_LAS unsigned*)(lds + (bufoff) + ldsw + _i * 8192), 16, (int)(voff)[_i], so_, 0, 0); } while (0)
; #define PG8_LDA(dst, b, h) do { _Pragma("unroll") for (int m = 0; m < 4; ++m) _Pragma("unroll") for (int k = 0; k < 2; ++k) dst[m][k] = *(const PG8_LAS bf16x8*)(lds + PG8_SA(b, h) + aoff + m * 2048 + k * 1024); } while (0)
; #define PG8_LDB(dst, b, h) do { _Pragma("unroll") for (int n = 0; n < 2; ++n) _Pragma("unroll") for (int k = 0; k < 2; ++k) dst[n][k] = *(const PG8_LAS bf16x8*)(lds + PG8_SB(b, h) + boff + n * 2048 + k * 1024); } while (0)
; #define PG8_MMA(ai, bj, At, Bt) do { __builtin_amdgcn_s_setprio(1); _Pragma("unroll") for (int m = 0; m < 4; ++m) _Pragma("unroll") for (int n = 0; n < 2; ++n) _Pragma("unroll") for (int k = 0; k < 2; ++k) \
;         acc[ai][bj][m][n] = __builtin_amdgcn_mfma_f32_16x16x32_bf16(Bt[n][k], At[m][k], acc[ai][bj][m][n], 0, 0, 0); __builtin_amdgcn_s_setprio(0); } while (0)
; template <class Epi, class Sched, bool ALIGN_EPI = false, bool SP2 = false>
; __device__ __forceinline__ void gemm_phase(PG8_LAS unsigned char* lds, const Gemm g, const Sched& S, const Epi& E, int tid_in) {
;     ...
;             PG8_LDB(B0, 0, 0); PG8_LDB(B1, 0, 1); PG8_SCHED; PG8_LDA(At, 0, 0); PG8_STAGE(PG8_SA(1, 1), a1 + hstepA, voffA);
;             PG8_WAIT_V(8); PG8_WAIT_L(0); PG8_BAR; PG8_MMA(0, 0, At, B0); PG8_MMA(0, 1, At, B1); PG8_BAR; PG8_SCHED;
;             PG8_LDA(At, 0, 1); PG8_STAGE(PG8_SB(0, 0), b2, voffB); PG8_STAGE(PG8_SB(0, 1), b2 + hstepB, voffB); PG8_STAGE(PG8_SA(0, 0), a2, voffA);
;             PG8_WAIT_V(8); PG8_WAIT_L(0); PG8_BAR; PG8_MMA(1, 0, At, B0); PG8_MMA(1, 1, At, B1); PG8_BAR; PG8_SCHED;
;             PG8_LDB(B0, 1, 0); PG8_LDB(B1, 1, 1); PG8_SCHED; PG8_LDA(At, 1, 0); PG8_STAGE(PG8_SA(0, 1), a2 + hstepA, voffA);
;             PG8_WAIT_V(8); PG8_WAIT_L(0); PG8_BAR; PG8_MMA(0, 0, At, B0); PG8_MMA(0, 1, At, B1); PG8_BAR; PG8_SCHED;
;             PG8_LDA(At, 1, 1); PG8_STAGE(PG8_SB(1, 0), b3, voffB); PG8_STAGE(PG8_SB(1, 1), b3 + hstepB, voffB); PG8_STAGE(PG8_SA(1, 0), a3, voffA);
;             PG8_WAIT_V(8); PG8_WAIT_L(0); PG8_BAR; PG8_MMA(1, 0, At, B0); PG8_MMA(1, 1, At, B1); PG8_BAR; PG8_SCHED;
	v_add_u32_e32 v0, 0x18000, v237
	ds_read_b128 v[130:133], v0
	ds_read_b128 v[134:137], v0 offset:1024
	ds_read_b128 v[138:141], v0 offset:2048
	ds_read_b128 v[142:145], v0 offset:3072
	v_add_u32_e32 v0, 0x1c000, v237
	ds_read_b128 v[146:149], v0
	ds_read_b128 v[150:153], v0 offset:1024
	ds_read_b128 v[154:157], v0 offset:2048
	ds_read_b128 v[158:161], v0 offset:3072
	s_add_i32 s36, s13, 0x80000
	s_mov_b32 m0, s73
	ds_read_b128 v[162:165], v238 offset:32768
	ds_read_b128 v[166:169], v238 offset:33792
	ds_read_b128 v[170:173], v238 offset:34816
	ds_read_b128 v[174:177], v238 offset:35840
	ds_read_b128 v[178:181], v238 offset:36864
	ds_read_b128 v[182:185], v238 offset:37888
	ds_read_b128 v[186:189], v238 offset:38912
	ds_read_b128 v[190:193], v238 offset:39936
	s_mov_b32 m0, s72
	s_nop 0
	buffer_load_dwordx4 v211, s[4:7], s13 offen lds
	s_mov_b32 m0, s73
	s_nop 0
	buffer_load_dwordx4 v195, s[4:7], s36 offen lds
	s_mov_b32 m0, s74
	s_nop 0
	buffer_load_dwordx4 v211, s[4:7], s36 offen lds
	s_waitcnt vmcnt(8)
	s_waitcnt lgkmcnt(0)
	s_barrier
	s_setprio 1
	s_waitcnt lgkmcnt(0)
	v_mfma_f32_16x16x32_bf16 v[126:129], v[130:133], v[162:165], v[126:129]
	v_mfma_f32_16x16x32_bf16 v[122:125], v[138:141], v[162:165], v[122:125]
	v_mfma_f32_16x16x32_bf16 v[110:113], v[130:133], v[170:173], v[110:113]
	v_mfma_f32_16x16x32_bf16 v[106:109], v[138:141], v[170:173], v[106:109]
	v_mfma_f32_16x16x32_bf16 v[94:97], v[130:133], v[178:181], v[94:97]
	v_mfma_f32_16x16x32_bf16 v[90:93], v[138:141], v[178:181], v[90:93]
	v_mfma_f32_16x16x32_bf16 v[78:81], v[130:133], v[186:189], v[78:81]
	v_mfma_f32_16x16x32_bf16 v[74:77], v[138:141], v[186:189], v[74:77]
	v_mfma_f32_16x16x32_bf16 v[126:129], v[134:137], v[166:169], v[126:129]
	v_mfma_f32_16x16x32_bf16 v[122:125], v[142:145], v[166:169], v[122:125]
	v_mfma_f32_16x16x32_bf16 v[110:113], v[134:137], v[174:177], v[110:113]
	v_mfma_f32_16x16x32_bf16 v[106:109], v[142:145], v[174:177], v[106:109]
	v_mfma_f32_16x16x32_bf16 v[94:97], v[134:137], v[182:185], v[94:97]
	v_mfma_f32_16x16x32_bf16 v[90:93], v[142:145], v[182:185], v[90:93]
	v_mfma_f32_16x16x32_bf16 v[78:81], v[134:137], v[190:193], v[78:81]
	v_mfma_f32_16x16x32_bf16 v[74:77], v[142:145], v[190:193], v[74:77]
	s_setprio 0
	s_setprio 1
	v_mfma_f32_16x16x32_bf16 v[118:121], v[146:149], v[162:165], v[118:121]
	v_mfma_f32_16x16x32_bf16 v[114:117], v[154:157], v[162:165], v[114:117]
	v_mfma_f32_16x16x32_bf16 v[102:105], v[146:149], v[170:173], v[102:105]
	v_mfma_f32_16x16x32_bf16 v[98:101], v[154:157], v[170:173], v[98:101]
	v_mfma_f32_16x16x32_bf16 v[86:89], v[146:149], v[178:181], v[86:89]
	v_mfma_f32_16x16x32_bf16 v[82:85], v[154:157], v[178:181], v[82:85]
	v_mfma_f32_16x16x32_bf16 v[70:73], v[146:149], v[186:189], v[70:73]
	v_mfma_f32_16x16x32_bf16 v[66:69], v[154:157], v[186:189], v[66:69]
	v_mfma_f32_16x16x32_bf16 v[118:121], v[150:153], v[166:169], v[118:121]
	v_mfma_f32_16x16x32_bf16 v[114:117], v[158:161], v[166:169], v[114:117]
	v_mfma_f32_16x16x32_bf16 v[102:105], v[150:153], v[174:177], v[102:105]
	v_mfma_f32_16x16x32_bf16 v[98:101], v[158:161], v[174:177], v[98:101]
	v_mfma_f32_16x16x32_bf16 v[86:89], v[150:153], v[182:185], v[86:89]
	v_mfma_f32_16x16x32_bf16 v[82:85], v[158:161], v[182:185], v[82:85]
	v_mfma_f32_16x16x32_bf16 v[70:73], v[150:153], v[190:193], v[70:73]
	v_mfma_f32_16x16x32_bf16 v[66:69], v[158:161], v[190:193], v[66:69]
	s_setprio 0
	s_barrier
	s_mov_b32 m0, s75
	s_add_i32 s36, s12, 0x80
	ds_read_b128 v[162:165], v238 offset:49152
	ds_read_b128 v[166:169], v238 offset:50176
	ds_read_b128 v[170:173], v238 offset:51200
	ds_read_b128 v[174:177], v238 offset:52224
	ds_read_b128 v[178:181], v238 offset:53248
	ds_read_b128 v[182:185], v238 offset:54272
	ds_read_b128 v[186:189], v238 offset:55296
	ds_read_b128 v[190:193], v238 offset:56320
	buffer_load_dwordx4 v207, s[40:43], s36 offen lds
	s_mov_b32 m0, s76
	s_add_i32 s12, s12, 0x80080
	buffer_load_dwordx4 v224, s[40:43], s36 offen lds
	s_mov_b32 m0, s79
	s_addk_i32 s13, 0x80
	buffer_load_dwordx4 v207, s[40:43], s12 offen lds
	s_mov_b32 m0, s68
	s_nop 0
	buffer_load_dwordx4 v224, s[40:43], s12 offen lds
	s_mov_b32 m0, s77
	s_nop 0
	buffer_load_dwordx4 v195, s[4:7], s13 offen lds
	s_waitcnt vmcnt(7)
	s_waitcnt lgkmcnt(0)
	s_barrier
	s_setprio 1
	s_waitcnt lgkmcnt(0)
	v_mfma_f32_16x16x32_bf16 v[62:65], v[130:133], v[162:165], v[62:65]
	v_mfma_f32_16x16x32_bf16 v[58:61], v[138:141], v[162:165], v[58:61]
	v_mfma_f32_16x16x32_bf16 v[46:49], v[130:133], v[170:173], v[46:49]
	v_mfma_f32_16x16x32_bf16 v[42:45], v[138:141], v[170:173], v[42:45]
	v_mfma_f32_16x16x32_bf16 v[30:33], v[130:133], v[178:181], v[30:33]
	v_mfma_f32_16x16x32_bf16 v[26:29], v[138:141], v[178:181], v[26:29]
	v_mfma_f32_16x16x32_bf16 v[14:17], v[130:133], v[186:189], v[14:17]
	v_mfma_f32_16x16x32_bf16 v[10:13], v[138:141], v[186:189], v[10:13]
	v_mfma_f32_16x16x32_bf16 v[62:65], v[134:137], v[166:169], v[62:65]
	v_mfma_f32_16x16x32_bf16 v[58:61], v[142:145], v[166:169], v[58:61]
	v_mfma_f32_16x16x32_bf16 v[46:49], v[134:137], v[174:177], v[46:49]
	v_mfma_f32_16x16x32_bf16 v[42:45], v[142:145], v[174:177], v[42:45]
	v_mfma_f32_16x16x32_bf16 v[30:33], v[134:137], v[182:185], v[30:33]
	v_mfma_f32_16x16x32_bf16 v[26:29], v[142:145], v[182:185], v[26:29]
	v_mfma_f32_16x16x32_bf16 v[14:17], v[134:137], v[190:193], v[14:17]
	v_mfma_f32_16x16x32_bf16 v[10:13], v[142:145], v[190:193], v[10:13]
	s_setprio 0
	s_setprio 1
	v_mfma_f32_16x16x32_bf16 v[54:57], v[146:149], v[162:165], v[54:57]
	v_mfma_f32_16x16x32_bf16 v[50:53], v[154:157], v[162:165], v[50:53]
	v_mfma_f32_16x16x32_bf16 v[38:41], v[146:149], v[170:173], v[38:41]
	v_mfma_f32_16x16x32_bf16 v[34:37], v[154:157], v[170:173], v[34:37]
	v_mfma_f32_16x16x32_bf16 v[22:25], v[146:149], v[178:181], v[22:25]
	v_mfma_f32_16x16x32_bf16 v[18:21], v[154:157], v[178:181], v[18:21]
	v_mfma_f32_16x16x32_bf16 v[6:9], v[146:149], v[186:189], v[6:9]
	v_mfma_f32_16x16x32_bf16 v[2:5], v[154:157], v[186:189], v[2:5]
	v_mfma_f32_16x16x32_bf16 v[54:57], v[150:153], v[166:169], v[54:57]
	v_mfma_f32_16x16x32_bf16 v[50:53], v[158:161], v[166:169], v[50:53]
	v_mfma_f32_16x16x32_bf16 v[38:41], v[150:153], v[174:177], v[38:41]
	v_mfma_f32_16x16x32_bf16 v[34:37], v[158:161], v[174:177], v[34:37]
	v_mfma_f32_16x16x32_bf16 v[22:25], v[150:153], v[182:185], v[22:25]
	v_mfma_f32_16x16x32_bf16 v[18:21], v[158:161], v[182:185], v[18:21]
	v_mfma_f32_16x16x32_bf16 v[6:9], v[150:153], v[190:193], v[6:9]
	v_mfma_f32_16x16x32_bf16 v[2:5], v[158:161], v[190:193], v[2:5]
	s_setprio 0
	s_barrier
	s_add_i32 s23, s23, 2
	s_add_u32 s20, s20, 0x100
	s_addc_u32 s21, s21, 0
	s_cmp_gt_u32 s23, 29
	s_mov_b64 s[12:13], s[16:17]
	s_cbranch_scc0 .LBB0_312
	s_and_b64 vcc, exec, s[48:49]
	s_cbranch_vccz .LBB0_315
	s_barrier

; #define PG8_STAGE(bufoff, gbase, voff) do { const int so_ = (int)(unsigned)((const char*)(gbase) - base_##voff); _Pragma("unroll") for (int _i = 0; _i < 2; ++_i) \
;         __builtin_amdgcn_raw_ptr_buffer_load_lds(rs_##voff, (PG8_LAS unsigned*)(lds + (bufoff) + ldsw + _i * 8192), 16, (int)(voff)[_i], so_, 0, 0); } while (0)
; #define PG8_LDA(dst, b, h) do { _Pragma("unroll") for (int m = 0; m < 4; ++m) _Pragma("unroll") for (int k = 0; k < 2; ++k) dst[m][k] = *(const PG8_LAS bf16x8*)(lds + PG8_SA(b, h) + aoff + m * 2048 + k * 1024); } while (0)
; #define PG8_LDB(dst, b, h) do { _Pragma("unroll") for (int n = 0; n < 2; ++n) _Pragma("unroll") for (int k = 0; k < 2; ++k) dst[n][k] = *(const PG8_LAS bf16x8*)(lds + PG8_SB(b, h) + boff + n * 2048 + k * 1024); } while (0)
; #define PG8_MMA(ai, bj, At, Bt) do { __builtin_amdgcn_s_setprio(1); _Pragma("unroll") for (int m = 0; m < 4; ++m) _Pragma("unroll") for (int n = 0; n < 2; ++n) _Pragma("unroll") for (int k = 0; k < 2; ++k) \
;         acc[ai][bj][m][n] = __builtin_amdgcn_mfma_f32_16x16x32_bf16(Bt[n][k], At[m][k], acc[ai][bj][m][n], 0, 0, 0); __builtin_amdgcn_s_setprio(0); } while (0)
; template <class Epi, class Sched, bool ALIGN_EPI = false, bool SP2 = false>
; __device__ __forceinline__ void gemm_phase(PG8_LAS unsigned char* lds, const Gemm g, const Sched& S, const Epi& E, int tid_in) {
;     ...
;             PG8_LDB(B0, 0, 0); PG8_LDB(B1, 0, 1); PG8_SCHED; PG8_LDA(At, 0, 0); PG8_STAGE(PG8_SA(1, 1), a1 + hstepA, voffA);
;             PG8_WAIT_V(8); PG8_WAIT_L(0); PG8_BAR; PG8_MMA(0, 0, At, B0); PG8_MMA(0, 1, At, B1); PG8_BAR; PG8_SCHED;
;             PG8_LDA(At, 0, 1); PG8_STAGE(PG8_SB(0, 0), b2, voffB); PG8_STAGE(PG8_SB(0, 1), b2 + hstepB, voffB); PG8_STAGE(PG8_SA(0, 0), a2, voffA);
;             PG8_WAIT_V(8); PG8_WAIT_L(0); PG8_BAR; PG8_MMA(1, 0, At, B0); PG8_MMA(1, 1, At, B1); PG8_BAR; PG8_SCHED;
;             PG8_LDB(B0, 1, 0); PG8_LDB(B1, 1, 1); PG8_SCHED; PG8_LDA(At, 1, 0); PG8_STAGE(PG8_SA(0, 1), a2 + hstepA, voffA);
;             PG8_WAIT_V(8); PG8_WAIT_L(0); PG8_BAR; PG8_MMA(0, 0, At, B0); PG8_MMA(0, 1, At, B1); PG8_BAR; PG8_SCHED;
;             PG8_LDA(At, 1, 1); PG8_STAGE(PG8_SB(1, 0), b3, voffB); PG8_STAGE(PG8_SB(1, 1), b3 + hstepB, voffB); PG8_STAGE(PG8_SA(1, 0), a3, voffA);
;             PG8_WAIT_V(8); PG8_WAIT_L(0); PG8_BAR; PG8_MMA(1, 0, At, B0); PG8_MMA(1, 1, At, B1); PG8_BAR; PG8_SCHED;
.LBB0_1037:
	v_add_u32_e32 v0, 0x10000, v236
	ds_read_b128 v[132:135], v0
	ds_read_b128 v[136:139], v0 offset:1024
	ds_read_b128 v[140:143], v0 offset:2048
	ds_read_b128 v[144:147], v0 offset:3072
	v_add_u32_e32 v0, 0x14000, v236
	ds_read_b128 v[148:151], v0
	ds_read_b128 v[152:155], v0 offset:1024
	ds_read_b128 v[156:159], v0 offset:2048
	ds_read_b128 v[160:163], v0 offset:3072
	s_add_u32 s16, s12, 0x100
	s_addc_u32 s17, s13, 0
	s_sub_i32 s12, s12, s4
	s_add_i32 s12, s12, 0xc0080
	s_sub_i32 s39, s12, 0xc0000
	s_cmp_eq_u32 s38, 12
	s_cselect_b32 s13, s24, s16
	s_mov_b32 m0, s76
	ds_read_b128 v[164:167], v237
	ds_read_b128 v[168:171], v237 offset:1024
	ds_read_b128 v[172:175], v237 offset:2048
	ds_read_b128 v[176:179], v237 offset:3072
	ds_read_b128 v[180:183], v237 offset:4096
	ds_read_b128 v[184:187], v237 offset:5120
	ds_read_b128 v[188:191], v237 offset:6144
	ds_read_b128 v[192:195], v237 offset:7168
	s_mov_b32 m0, s73
	s_nop 0
	buffer_load_dwordx4 v222, s[4:7], s39 offen lds
	s_mov_b32 m0, s76
	s_nop 0
	buffer_load_dwordx4 v220, s[4:7], s12 offen lds
	s_mov_b32 m0, s77
	s_nop 0
	buffer_load_dwordx4 v222, s[4:7], s12 offen lds
	s_waitcnt vmcnt(8)
	s_waitcnt lgkmcnt(0)
	s_barrier
	s_setprio 1
	s_waitcnt lgkmcnt(0)
	v_mfma_f32_16x16x32_bf16 v[128:131], v[132:135], v[164:167], v[128:131]
	v_mfma_f32_16x16x32_bf16 v[124:127], v[140:143], v[164:167], v[124:127]
	v_mfma_f32_16x16x32_bf16 v[120:123], v[132:135], v[172:175], v[120:123]
	v_mfma_f32_16x16x32_bf16 v[116:119], v[140:143], v[172:175], v[116:119]
	v_mfma_f32_16x16x32_bf16 v[112:115], v[132:135], v[180:183], v[112:115]
	v_mfma_f32_16x16x32_bf16 v[108:111], v[140:143], v[180:183], v[108:111]
	v_mfma_f32_16x16x32_bf16 v[104:107], v[132:135], v[188:191], v[104:107]
	v_mfma_f32_16x16x32_bf16 v[100:103], v[140:143], v[188:191], v[100:103]
	v_mfma_f32_16x16x32_bf16 v[128:131], v[136:139], v[168:171], v[128:131]
	v_mfma_f32_16x16x32_bf16 v[124:127], v[144:147], v[168:171], v[124:127]
	v_mfma_f32_16x16x32_bf16 v[120:123], v[136:139], v[176:179], v[120:123]
	v_mfma_f32_16x16x32_bf16 v[116:119], v[144:147], v[176:179], v[116:119]
	v_mfma_f32_16x16x32_bf16 v[112:115], v[136:139], v[184:187], v[112:115]
	v_mfma_f32_16x16x32_bf16 v[108:111], v[144:147], v[184:187], v[108:111]
	v_mfma_f32_16x16x32_bf16 v[104:107], v[136:139], v[192:195], v[104:107]
	v_mfma_f32_16x16x32_bf16 v[100:103], v[144:147], v[192:195], v[100:103]
	s_setprio 0
	s_setprio 1
	v_mfma_f32_16x16x32_bf16 v[96:99], v[148:151], v[164:167], v[96:99]
	v_mfma_f32_16x16x32_bf16 v[92:95], v[156:159], v[164:167], v[92:95]
	v_mfma_f32_16x16x32_bf16 v[88:91], v[148:151], v[172:175], v[88:91]
	v_mfma_f32_16x16x32_bf16 v[84:87], v[156:159], v[172:175], v[84:87]
	v_mfma_f32_16x16x32_bf16 v[80:83], v[148:151], v[180:183], v[80:83]
	v_mfma_f32_16x16x32_bf16 v[76:79], v[156:159], v[180:183], v[76:79]
	v_mfma_f32_16x16x32_bf16 v[72:75], v[148:151], v[188:191], v[72:75]
	v_mfma_f32_16x16x32_bf16 v[68:71], v[156:159], v[188:191], v[68:71]
	v_mfma_f32_16x16x32_bf16 v[96:99], v[152:155], v[168:171], v[96:99]
	v_mfma_f32_16x16x32_bf16 v[92:95], v[160:163], v[168:171], v[92:95]
	v_mfma_f32_16x16x32_bf16 v[88:91], v[152:155], v[176:179], v[88:91]
	v_mfma_f32_16x16x32_bf16 v[84:87], v[160:163], v[176:179], v[84:87]
	v_mfma_f32_16x16x32_bf16 v[80:83], v[152:155], v[184:187], v[80:83]
	v_mfma_f32_16x16x32_bf16 v[76:79], v[160:163], v[184:187], v[76:79]
	v_mfma_f32_16x16x32_bf16 v[72:75], v[152:155], v[192:195], v[72:75]
	v_mfma_f32_16x16x32_bf16 v[68:71], v[160:163], v[192:195], v[68:71]
	s_setprio 0
	s_barrier
	s_cselect_b32 s12, s18, s19
	s_mov_b32 m0, s26
	s_mov_b32 s46, s6
	s_mov_b32 s47, s7
	s_sub_i32 s12, s12, s44
	ds_read_b128 v[164:167], v237 offset:16384
	ds_read_b128 v[168:171], v237 offset:17408
	ds_read_b128 v[172:175], v237 offset:18432
	ds_read_b128 v[176:179], v237 offset:19456
	ds_read_b128 v[180:183], v237 offset:20480
	ds_read_b128 v[184:187], v237 offset:21504
	ds_read_b128 v[188:191], v237 offset:22528
	ds_read_b128 v[192:195], v237 offset:23552
	buffer_load_dwordx4 v221, s[44:47], s12 offen lds
	s_mov_b32 m0, s53
	s_add_i32 s39, s12, 0x40000
	buffer_load_dwordx4 v223, s[44:47], s12 offen lds
	s_mov_b32 m0, s60
	s_sub_i32 s13, s13, s4
	buffer_load_dwordx4 v221, s[44:47], s39 offen lds
	s_mov_b32 m0, s61
	s_nop 0
	buffer_load_dwordx4 v223, s[44:47], s39 offen lds
	s_mov_b32 m0, s21
	s_nop 0
	buffer_load_dwordx4 v220, s[4:7], s13 offen lds
	s_waitcnt vmcnt(7)
	s_waitcnt lgkmcnt(0)
	s_barrier
	s_setprio 1
	s_waitcnt lgkmcnt(0)
	v_mfma_f32_16x16x32_bf16 v[64:67], v[132:135], v[164:167], v[64:67]
	v_mfma_f32_16x16x32_bf16 v[60:63], v[140:143], v[164:167], v[60:63]
	v_mfma_f32_16x16x32_bf16 v[56:59], v[132:135], v[172:175], v[56:59]
	v_mfma_f32_16x16x32_bf16 v[52:55], v[140:143], v[172:175], v[52:55]
	v_mfma_f32_16x16x32_bf16 v[48:51], v[132:135], v[180:183], v[48:51]
	v_mfma_f32_16x16x32_bf16 v[44:47], v[140:143], v[180:183], v[44:47]
	v_mfma_f32_16x16x32_bf16 v[40:43], v[132:135], v[188:191], v[40:43]
	v_mfma_f32_16x16x32_bf16 v[36:39], v[140:143], v[188:191], v[36:39]
	v_mfma_f32_16x16x32_bf16 v[64:67], v[136:139], v[168:171], v[64:67]
	v_mfma_f32_16x16x32_bf16 v[60:63], v[144:147], v[168:171], v[60:63]
	v_mfma_f32_16x16x32_bf16 v[56:59], v[136:139], v[176:179], v[56:59]
	v_mfma_f32_16x16x32_bf16 v[52:55], v[144:147], v[176:179], v[52:55]
	v_mfma_f32_16x16x32_bf16 v[48:51], v[136:139], v[184:187], v[48:51]
	v_mfma_f32_16x16x32_bf16 v[44:47], v[144:147], v[184:187], v[44:47]
	v_mfma_f32_16x16x32_bf16 v[40:43], v[136:139], v[192:195], v[40:43]
	v_mfma_f32_16x16x32_bf16 v[36:39], v[144:147], v[192:195], v[36:39]
	s_setprio 0
	s_setprio 1
	v_mfma_f32_16x16x32_bf16 v[32:35], v[148:151], v[164:167], v[32:35]
	v_mfma_f32_16x16x32_bf16 v[28:31], v[156:159], v[164:167], v[28:31]
	v_mfma_f32_16x16x32_bf16 v[24:27], v[148:151], v[172:175], v[24:27]
	v_mfma_f32_16x16x32_bf16 v[20:23], v[156:159], v[172:175], v[20:23]
	v_mfma_f32_16x16x32_bf16 v[16:19], v[148:151], v[180:183], v[16:19]
	v_mfma_f32_16x16x32_bf16 v[12:15], v[156:159], v[180:183], v[12:15]
	v_mfma_f32_16x16x32_bf16 v[8:11], v[148:151], v[188:191], v[8:11]
	v_mfma_f32_16x16x32_bf16 v[2:5], v[156:159], v[188:191], v[4:7]
	v_mfma_f32_16x16x32_bf16 v[32:35], v[152:155], v[168:171], v[32:35]
	v_mfma_f32_16x16x32_bf16 v[28:31], v[160:163], v[168:171], v[28:31]
	v_mfma_f32_16x16x32_bf16 v[24:27], v[152:155], v[176:179], v[24:27]
	v_mfma_f32_16x16x32_bf16 v[20:23], v[160:163], v[176:179], v[20:23]
	v_mfma_f32_16x16x32_bf16 v[16:19], v[152:155], v[184:187], v[16:19]
	v_mfma_f32_16x16x32_bf16 v[12:15], v[160:163], v[184:187], v[12:15]
	v_mfma_f32_16x16x32_bf16 v[8:11], v[152:155], v[192:195], v[8:11]
	v_mfma_f32_16x16x32_bf16 v[2:5], v[160:163], v[192:195], v[2:5]
	s_setprio 0
	s_barrier
; template <class Epi, class Sched, bool ALIGN_EPI = false, bool SP2 = false>
; __device__ __forceinline__ void gemm_phase(PG8_LAS unsigned char* lds, const Gemm g, const Sched& S, const Epi& E, int tid_in) {
;     ...
;             PG8_LDB(B0, 0, 0); PG8_LDB(B1, 0, 1); PG8_SCHED; PG8_LDA(At, 0, 0); PG8_STAGE(PG8_SA(1, 1), a1 + hstepA, voffA);
;             PG8_WAIT_V(8); PG8_WAIT_L(0); PG8_BAR; PG8_MMA(0, 0, At, B0); PG8_MMA(0, 1, At, B1); PG8_BAR; PG8_SCHED;
;             PG8_LDA(At, 0, 1); PG8_STAGE(PG8_SB(0, 0), b2, voffB); PG8_STAGE(PG8_SB(0, 1), b2 + hstepB, voffB); PG8_STAGE(PG8_SA(0, 0), a2, voffA);
;             PG8_WAIT_V(8); PG8_WAIT_L(0); PG8_BAR; PG8_MMA(1, 0, At, B0); PG8_MMA(1, 1, At, B1); PG8_BAR; PG8_SCHED;
;             PG8_LDB(B0, 1, 0); PG8_LDB(B1, 1, 1); PG8_SCHED; PG8_LDA(At, 1, 0); PG8_STAGE(PG8_SA(0, 1), a2 + hstepA, voffA);
;             PG8_WAIT_V(8); PG8_WAIT_L(0); PG8_BAR; PG8_MMA(0, 0, At, B0); PG8_MMA(0, 1, At, B1); PG8_BAR; PG8_SCHED;
;             PG8_LDA(At, 1, 1); PG8_STAGE(PG8_SB(1, 0), b3, voffB); PG8_STAGE(PG8_SB(1, 1), b3 + hstepB, voffB); PG8_STAGE(PG8_SA(1, 0), a3, voffA);
;             PG8_WAIT_V(8); PG8_WAIT_L(0); PG8_BAR; PG8_MMA(1, 0, At, B0); PG8_MMA(1, 1, At, B1); PG8_BAR; PG8_SCHED;
;             } else {
;             PG8_LDB(B0, 0, 0); PG8_SCHED; PG8_LDA(At, 0, 0); PG8_STAGE(PG8_SA(1, 1), a1 + hstepA, voffA);
;             PG8_WAIT_L(8); PG8_BAR; PG8_WAIT_L(0); PG8_MMA(0, 0, At, B0); PG8_BAR; PG8_SCHED;
;             PG8_LDB(B1, 0, 1); PG8_STAGE(PG8_SB(0, 0), b2, voffB);
;             PG8_BAR; PG8_WAIT_L(0); PG8_MMA(0, 1, At, B1); PG8_BAR;
;             PG8_LDA(At, 0, 1); PG8_STAGE(PG8_SA(0, 0), a2, voffA);
;             PG8_BAR; PG8_WAIT_L(0); PG8_MMA(1, 0, At, B0); PG8_BAR; PG8_SCHED;
;             PG8_STAGE(PG8_SB(0, 1), b2 + hstepB, voffB);
;             PG8_WAIT_V(6); PG8_BAR; PG8_MMA(1, 1, At, B1); PG8_BAR;
;             PG8_LDB(B0, 1, 0); PG8_SCHED; PG8_LDA(At, 1, 0); PG8_STAGE(PG8_SA(0, 1), a2 + hstepA, voffA);
;             PG8_WAIT_L(8); PG8_BAR; PG8_WAIT_L(0); PG8_MMA(0, 0, At, B0); PG8_BAR; PG8_SCHED;
;             PG8_LDB(B1, 1, 1); PG8_STAGE(PG8_SB(1, 0), b3, voffB);
;             PG8_BAR; PG8_WAIT_L(0); PG8_MMA(0, 1, At, B1); PG8_BAR;
;             PG8_LDA(At, 1, 1); PG8_STAGE(PG8_SA(1, 0), a3, voffA);
;             PG8_BAR; PG8_WAIT_L(0); PG8_MMA(1, 0, At, B0); PG8_BAR; PG8_SCHED;
	v_add_u32_e32 v0, 0x18000, v236
	ds_read_b128 v[132:135], v0
	ds_read_b128 v[136:139], v0 offset:1024
	ds_read_b128 v[140:143], v0 offset:2048
	ds_read_b128 v[144:147], v0 offset:3072
	v_add_u32_e32 v0, 0x1c000, v236
	ds_read_b128 v[148:151], v0
	ds_read_b128 v[152:155], v0 offset:1024
	ds_read_b128 v[156:159], v0 offset:2048
	ds_read_b128 v[160:163], v0 offset:3072
	s_add_i32 s39, s13, 0xc0000
	s_mov_b32 m0, s63
	ds_read_b128 v[164:167], v237 offset:32768
	ds_read_b128 v[168:171], v237 offset:33792
	ds_read_b128 v[172:175], v237 offset:34816
	ds_read_b128 v[176:179], v237 offset:35840
	ds_read_b128 v[180:183], v237 offset:36864
	ds_read_b128 v[184:187], v237 offset:37888
	ds_read_b128 v[188:191], v237 offset:38912
	ds_read_b128 v[192:195], v237 offset:39936
	s_mov_b32 m0, s62
	s_nop 0
	buffer_load_dwordx4 v222, s[4:7], s13 offen lds
	s_mov_b32 m0, s63
	s_nop 0
	buffer_load_dwordx4 v220, s[4:7], s39 offen lds
	s_mov_b32 m0, s66
	s_nop 0
	buffer_load_dwordx4 v222, s[4:7], s39 offen lds
	s_waitcnt vmcnt(8)
	s_waitcnt lgkmcnt(0)
	s_barrier
	s_setprio 1
	s_waitcnt lgkmcnt(0)
	v_mfma_f32_16x16x32_bf16 v[128:131], v[132:135], v[164:167], v[128:131]
	v_mfma_f32_16x16x32_bf16 v[124:127], v[140:143], v[164:167], v[124:127]
	v_mfma_f32_16x16x32_bf16 v[120:123], v[132:135], v[172:175], v[120:123]
	v_mfma_f32_16x16x32_bf16 v[116:119], v[140:143], v[172:175], v[116:119]
	v_mfma_f32_16x16x32_bf16 v[112:115], v[132:135], v[180:183], v[112:115]
	v_mfma_f32_16x16x32_bf16 v[108:111], v[140:143], v[180:183], v[108:111]
	v_mfma_f32_16x16x32_bf16 v[104:107], v[132:135], v[188:191], v[104:107]
	v_mfma_f32_16x16x32_bf16 v[100:103], v[140:143], v[188:191], v[100:103]
	v_mfma_f32_16x16x32_bf16 v[128:131], v[136:139], v[168:171], v[128:131]
	v_mfma_f32_16x16x32_bf16 v[124:127], v[144:147], v[168:171], v[124:127]
	v_mfma_f32_16x16x32_bf16 v[120:123], v[136:139], v[176:179], v[120:123]
	v_mfma_f32_16x16x32_bf16 v[116:119], v[144:147], v[176:179], v[116:119]
	v_mfma_f32_16x16x32_bf16 v[112:115], v[136:139], v[184:187], v[112:115]
	v_mfma_f32_16x16x32_bf16 v[108:111], v[144:147], v[184:187], v[108:111]
	v_mfma_f32_16x16x32_bf16 v[104:107], v[136:139], v[192:195], v[104:107]
	v_mfma_f32_16x16x32_bf16 v[100:103], v[144:147], v[192:195], v[100:103]
	s_setprio 0
	s_setprio 1
	v_mfma_f32_16x16x32_bf16 v[96:99], v[148:151], v[164:167], v[96:99]
	v_mfma_f32_16x16x32_bf16 v[92:95], v[156:159], v[164:167], v[92:95]
	v_mfma_f32_16x16x32_bf16 v[88:91], v[148:151], v[172:175], v[88:91]
	v_mfma_f32_16x16x32_bf16 v[84:87], v[156:159], v[172:175], v[84:87]
	v_mfma_f32_16x16x32_bf16 v[80:83], v[148:151], v[180:183], v[80:83]
	v_mfma_f32_16x16x32_bf16 v[76:79], v[156:159], v[180:183], v[76:79]
	v_mfma_f32_16x16x32_bf16 v[72:75], v[148:151], v[188:191], v[72:75]
	v_mfma_f32_16x16x32_bf16 v[68:71], v[156:159], v[188:191], v[68:71]
	v_mfma_f32_16x16x32_bf16 v[96:99], v[152:155], v[168:171], v[96:99]
	v_mfma_f32_16x16x32_bf16 v[92:95], v[160:163], v[168:171], v[92:95]
	v_mfma_f32_16x16x32_bf16 v[88:91], v[152:155], v[176:179], v[88:91]
	v_mfma_f32_16x16x32_bf16 v[84:87], v[160:163], v[176:179], v[84:87]
	v_mfma_f32_16x16x32_bf16 v[80:83], v[152:155], v[184:187], v[80:83]
	v_mfma_f32_16x16x32_bf16 v[76:79], v[160:163], v[184:187], v[76:79]
	v_mfma_f32_16x16x32_bf16 v[72:75], v[152:155], v[192:195], v[72:75]
	v_mfma_f32_16x16x32_bf16 v[68:71], v[160:163], v[192:195], v[68:71]
	s_setprio 0
	s_barrier
	s_mov_b32 m0, s69
	s_add_i32 s39, s12, 0x80
	ds_read_b128 v[164:167], v237 offset:49152
	ds_read_b128 v[168:171], v237 offset:50176
	ds_read_b128 v[172:175], v237 offset:51200
	ds_read_b128 v[176:179], v237 offset:52224
	ds_read_b128 v[180:183], v237 offset:53248
	ds_read_b128 v[184:187], v237 offset:54272
	ds_read_b128 v[188:191], v237 offset:55296
	ds_read_b128 v[192:195], v237 offset:56320
	buffer_load_dwordx4 v221, s[44:47], s39 offen lds
	s_mov_b32 m0, s71
	s_add_i32 s12, s12, 0x40080
	buffer_load_dwordx4 v223, s[44:47], s39 offen lds
	s_mov_b32 m0, s74
	s_addk_i32 s13, 0x80
	buffer_load_dwordx4 v221, s[44:47], s12 offen lds
	s_mov_b32 m0, s75
	s_nop 0
	buffer_load_dwordx4 v223, s[44:47], s12 offen lds
	s_mov_b32 m0, s72
	s_nop 0
	buffer_load_dwordx4 v220, s[4:7], s13 offen lds
	s_waitcnt vmcnt(7)
	s_waitcnt lgkmcnt(0)
	s_barrier
	s_setprio 1
	s_waitcnt lgkmcnt(0)
	v_mfma_f32_16x16x32_bf16 v[64:67], v[132:135], v[164:167], v[64:67]
	v_mfma_f32_16x16x32_bf16 v[60:63], v[140:143], v[164:167], v[60:63]
	v_mfma_f32_16x16x32_bf16 v[56:59], v[132:135], v[172:175], v[56:59]
	v_mfma_f32_16x16x32_bf16 v[52:55], v[140:143], v[172:175], v[52:55]
	v_mfma_f32_16x16x32_bf16 v[48:51], v[132:135], v[180:183], v[48:51]
	v_mfma_f32_16x16x32_bf16 v[44:47], v[140:143], v[180:183], v[44:47]
	v_mfma_f32_16x16x32_bf16 v[40:43], v[132:135], v[188:191], v[40:43]
	v_mfma_f32_16x16x32_bf16 v[36:39], v[140:143], v[188:191], v[36:39]
	v_mfma_f32_16x16x32_bf16 v[64:67], v[136:139], v[168:171], v[64:67]
	v_mfma_f32_16x16x32_bf16 v[60:63], v[144:147], v[168:171], v[60:63]
	v_mfma_f32_16x16x32_bf16 v[56:59], v[136:139], v[176:179], v[56:59]
	v_mfma_f32_16x16x32_bf16 v[52:55], v[144:147], v[176:179], v[52:55]
	v_mfma_f32_16x16x32_bf16 v[48:51], v[136:139], v[184:187], v[48:51]
	v_mfma_f32_16x16x32_bf16 v[44:47], v[144:147], v[184:187], v[44:47]
	v_mfma_f32_16x16x32_bf16 v[40:43], v[136:139], v[192:195], v[40:43]
	v_mfma_f32_16x16x32_bf16 v[36:39], v[144:147], v[192:195], v[36:39]
	s_setprio 0
	s_setprio 1
	v_mfma_f32_16x16x32_bf16 v[32:35], v[148:151], v[164:167], v[32:35]
	v_mfma_f32_16x16x32_bf16 v[28:31], v[156:159], v[164:167], v[28:31]
	v_mfma_f32_16x16x32_bf16 v[24:27], v[148:151], v[172:175], v[24:27]
	v_mfma_f32_16x16x32_bf16 v[20:23], v[156:159], v[172:175], v[20:23]
	v_mfma_f32_16x16x32_bf16 v[16:19], v[148:151], v[180:183], v[16:19]
	v_mfma_f32_16x16x32_bf16 v[12:15], v[156:159], v[180:183], v[12:15]
	v_mfma_f32_16x16x32_bf16 v[6:9], v[148:151], v[188:191], v[8:11]
	v_mfma_f32_16x16x32_bf16 v[2:5], v[156:159], v[188:191], v[2:5]
	v_mfma_f32_16x16x32_bf16 v[32:35], v[152:155], v[168:171], v[32:35]
	v_mfma_f32_16x16x32_bf16 v[28:31], v[160:163], v[168:171], v[28:31]
	v_mfma_f32_16x16x32_bf16 v[24:27], v[152:155], v[176:179], v[24:27]
	v_mfma_f32_16x16x32_bf16 v[20:23], v[160:163], v[176:179], v[20:23]
	v_mfma_f32_16x16x32_bf16 v[16:19], v[152:155], v[184:187], v[16:19]
	v_mfma_f32_16x16x32_bf16 v[12:15], v[160:163], v[184:187], v[12:15]
	v_mfma_f32_16x16x32_bf16 v[8:11], v[152:155], v[192:195], v[6:9]
	v_mfma_f32_16x16x32_bf16 v[4:7], v[160:163], v[192:195], v[2:5]
	s_setprio 0
	s_barrier
	s_add_i32 s38, s38, 2
	s_add_u32 s19, s19, 0x100
	s_addc_u32 s23, s23, 0
	s_cmp_gt_u32 s38, 13
	s_mov_b64 s[12:13], s[16:17]
	s_cbranch_scc0 .LBB0_1037
	s_and_b64 vcc, exec, s[14:15]
	s_cbranch_vccz .LBB0_1040
	s_barrier

; #define PG8_STAGE(bufoff, gbase, voff) do { const int so_ = (int)(unsigned)((const char*)(gbase) - base_##voff); _Pragma("unroll") for (int _i = 0; _i < 2; ++_i) \
;         __builtin_amdgcn_raw_ptr_buffer_load_lds(rs_##voff, (PG8_LAS unsigned*)(lds + (bufoff) + ldsw + _i * 8192), 16, (int)(voff)[_i], so_, 0, 0); } while (0)
; #define PG8_LDA(dst, b, h) do { _Pragma("unroll") for (int m = 0; m < 4; ++m) _Pragma("unroll") for (int k = 0; k < 2; ++k) dst[m][k] = *(const PG8_LAS bf16x8*)(lds + PG8_SA(b, h) + aoff + m * 2048 + k * 1024); } while (0)
; #define PG8_LDB(dst, b, h) do { _Pragma("unroll") for (int n = 0; n < 2; ++n) _Pragma("unroll") for (int k = 0; k < 2; ++k) dst[n][k] = *(const PG8_LAS bf16x8*)(lds + PG8_SB(b, h) + boff + n * 2048 + k * 1024); } while (0)
; #define PG8_MMA(ai, bj, At, Bt) do { __builtin_amdgcn_s_setprio(1); _Pragma("unroll") for (int m = 0; m < 4; ++m) _Pragma("unroll") for (int n = 0; n < 2; ++n) _Pragma("unroll") for (int k = 0; k < 2; ++k) \
;         acc[ai][bj][m][n] = __builtin_amdgcn_mfma_f32_16x16x32_bf16(Bt[n][k], At[m][k], acc[ai][bj][m][n], 0, 0, 0); __builtin_amdgcn_s_setprio(0); } while (0)
; template <class Epi, class Sched, bool ALIGN_EPI = false, bool SP2 = false>
; __device__ __forceinline__ void gemm_phase(PG8_LAS unsigned char* lds, const Gemm g, const Sched& S, const Epi& E, int tid_in) {
;     ...
;             PG8_LDB(B0, 0, 0); PG8_LDB(B1, 0, 1); PG8_SCHED; PG8_LDA(At, 0, 0); PG8_STAGE(PG8_SA(1, 1), a1 + hstepA, voffA);
;             PG8_WAIT_V(8); PG8_WAIT_L(0); PG8_BAR; PG8_MMA(0, 0, At, B0); PG8_MMA(0, 1, At, B1); PG8_BAR; PG8_SCHED;
;             PG8_LDA(At, 0, 1); PG8_STAGE(PG8_SB(0, 0), b2, voffB); PG8_STAGE(PG8_SB(0, 1), b2 + hstepB, voffB); PG8_STAGE(PG8_SA(0, 0), a2, voffA);
;             PG8_WAIT_V(8); PG8_WAIT_L(0); PG8_BAR; PG8_MMA(1, 0, At, B0); PG8_MMA(1, 1, At, B1); PG8_BAR; PG8_SCHED;
;             PG8_LDB(B0, 1, 0); PG8_LDB(B1, 1, 1); PG8_SCHED; PG8_LDA(At, 1, 0); PG8_STAGE(PG8_SA(0, 1), a2 + hstepA, voffA);
;             PG8_WAIT_V(8); PG8_WAIT_L(0); PG8_BAR; PG8_MMA(0, 0, At, B0); PG8_MMA(0, 1, At, B1); PG8_BAR; PG8_SCHED;
;             PG8_LDA(At, 1, 1); PG8_STAGE(PG8_SB(1, 0), b3, voffB); PG8_STAGE(PG8_SB(1, 1), b3 + hstepB, voffB); PG8_STAGE(PG8_SA(1, 0), a3, voffA);
;             PG8_WAIT_V(8); PG8_WAIT_L(0); PG8_BAR; PG8_MMA(1, 0, At, B0); PG8_MMA(1, 1, At, B1); PG8_BAR; PG8_SCHED;
.LBB0_1265:
	v_add_u32_e32 v133, 0x10000, v131
	ds_read_b128 v[134:137], v133
	ds_read_b128 v[138:141], v133 offset:1024
	ds_read_b128 v[142:145], v133 offset:2048
	ds_read_b128 v[146:149], v133 offset:3072
	v_add_u32_e32 v133, 0x14000, v131
	ds_read_b128 v[150:153], v133
	ds_read_b128 v[154:157], v133 offset:1024
	ds_read_b128 v[158:161], v133 offset:2048
	ds_read_b128 v[166:169], v133 offset:3072
	s_add_i32 s42, s18, s44
	s_add_i32 s21, s14, s44
	s_add_i32 s79, s12, s44
	s_addk_i32 s42, 0xff80
	s_sub_i32 vcc_lo, s42, 0x80000
	s_cmp_eq_u32 s19, 28
	s_cselect_b32 s21, s15, s21
	s_mov_b32 m0, s75
	ds_read_b128 v[170:173], v132
	ds_read_b128 v[174:177], v132 offset:1024
	ds_read_b128 v[178:181], v132 offset:2048
	ds_read_b128 v[182:185], v132 offset:3072
	ds_read_b128 v[186:189], v132 offset:4096
	ds_read_b128 v[190:193], v132 offset:5120
	ds_read_b128 v[200:203], v132 offset:6144
	ds_read_b128 v[206:209], v132 offset:7168
	s_mov_b32 m0, s72
	s_nop 0
	buffer_load_dwordx4 v130, s[4:7], vcc_lo offen lds
	s_mov_b32 m0, s75
	s_nop 0
	buffer_load_dwordx4 v0, s[4:7], s42 offen lds
	s_mov_b32 m0, s76
	s_nop 0
	buffer_load_dwordx4 v130, s[4:7], s42 offen lds
	s_waitcnt vmcnt(8)
	s_waitcnt lgkmcnt(0)
	s_barrier
	s_setprio 1
	s_waitcnt lgkmcnt(0)
	v_mfma_f32_16x16x32_bf16 v[34:37], v[134:137], v[170:173], v[34:37]
	v_mfma_f32_16x16x32_bf16 v[18:21], v[142:145], v[170:173], v[18:21]
	v_mfma_f32_16x16x32_bf16 v[86:89], v[134:137], v[178:181], v[86:89]
	v_mfma_f32_16x16x32_bf16 v[78:81], v[142:145], v[178:181], v[78:81]
	v_mfma_f32_16x16x32_bf16 v[106:109], v[134:137], v[186:189], v[106:109]
	v_mfma_f32_16x16x32_bf16 v[102:105], v[142:145], v[186:189], v[102:105]
	v_mfma_f32_16x16x32_bf16 v[126:129], v[134:137], v[200:203], v[126:129]
	v_mfma_f32_16x16x32_bf16 v[122:125], v[142:145], v[200:203], v[122:125]
	v_mfma_f32_16x16x32_bf16 v[34:37], v[138:141], v[174:177], v[34:37]
	v_mfma_f32_16x16x32_bf16 v[18:21], v[146:149], v[174:177], v[18:21]
	v_mfma_f32_16x16x32_bf16 v[86:89], v[138:141], v[182:185], v[86:89]
	v_mfma_f32_16x16x32_bf16 v[78:81], v[146:149], v[182:185], v[78:81]
	v_mfma_f32_16x16x32_bf16 v[106:109], v[138:141], v[190:193], v[106:109]
	v_mfma_f32_16x16x32_bf16 v[102:105], v[146:149], v[190:193], v[102:105]
	v_mfma_f32_16x16x32_bf16 v[126:129], v[138:141], v[206:209], v[126:129]
	v_mfma_f32_16x16x32_bf16 v[122:125], v[146:149], v[206:209], v[122:125]
	s_setprio 0
	s_setprio 1
	v_mfma_f32_16x16x32_bf16 v[14:17], v[150:153], v[170:173], v[14:17]
	v_mfma_f32_16x16x32_bf16 v[38:41], v[158:161], v[170:173], v[38:41]
	v_mfma_f32_16x16x32_bf16 v[74:77], v[150:153], v[178:181], v[74:77]
	v_mfma_f32_16x16x32_bf16 v[90:93], v[158:161], v[178:181], v[90:93]
	v_mfma_f32_16x16x32_bf16 v[98:101], v[150:153], v[186:189], v[98:101]
	v_mfma_f32_16x16x32_bf16 v[110:113], v[158:161], v[186:189], v[110:113]
	v_mfma_f32_16x16x32_bf16 v[118:121], v[150:153], v[200:203], v[118:121]
	v_mfma_f32_16x16x32_bf16 v[114:117], v[158:161], v[200:203], v[114:117]
	v_mfma_f32_16x16x32_bf16 v[14:17], v[154:157], v[174:177], v[14:17]
	v_mfma_f32_16x16x32_bf16 v[38:41], v[166:169], v[174:177], v[38:41]
	v_mfma_f32_16x16x32_bf16 v[74:77], v[154:157], v[182:185], v[74:77]
	v_mfma_f32_16x16x32_bf16 v[90:93], v[166:169], v[182:185], v[90:93]
	v_mfma_f32_16x16x32_bf16 v[98:101], v[154:157], v[190:193], v[98:101]
	v_mfma_f32_16x16x32_bf16 v[110:113], v[166:169], v[190:193], v[110:113]
	v_mfma_f32_16x16x32_bf16 v[118:121], v[154:157], v[206:209], v[118:121]
	v_mfma_f32_16x16x32_bf16 v[114:117], v[166:169], v[206:209], v[114:117]
	s_setprio 0
	s_barrier
	s_cselect_b32 s79, s17, s79
	s_mov_b32 m0, s49
	s_mov_b32 s42, s6
	s_mov_b32 s43, s7
	s_sub_i32 s79, s79, s40
	ds_read_b128 v[170:173], v132 offset:16384
	ds_read_b128 v[174:177], v132 offset:17408
	ds_read_b128 v[178:181], v132 offset:18432
	ds_read_b128 v[182:185], v132 offset:19456
	ds_read_b128 v[186:189], v132 offset:20480
	ds_read_b128 v[190:193], v132 offset:21504
	ds_read_b128 v[200:203], v132 offset:22528
	ds_read_b128 v[206:209], v132 offset:23552
	buffer_load_dwordx4 v0, s[40:43], s79 offen lds
	s_mov_b32 m0, s60
	s_add_i32 vcc_lo, s79, 0x80000
	buffer_load_dwordx4 v130, s[40:43], s79 offen lds
	s_mov_b32 m0, s61
	s_sub_i32 s21, s21, s4
	buffer_load_dwordx4 v0, s[40:43], vcc_lo offen lds
	s_mov_b32 m0, s62
	s_nop 0
	buffer_load_dwordx4 v130, s[40:43], vcc_lo offen lds
	s_mov_b32 m0, s35
	s_nop 0
	buffer_load_dwordx4 v0, s[4:7], s21 offen lds
	s_waitcnt vmcnt(7)
	s_waitcnt lgkmcnt(0)
	s_barrier
	s_setprio 1
	s_waitcnt lgkmcnt(0)
	v_mfma_f32_16x16x32_bf16 v[50:53], v[134:137], v[170:173], v[50:53]
	v_mfma_f32_16x16x32_bf16 v[30:33], v[142:145], v[170:173], v[30:33]
	v_mfma_f32_16x16x32_bf16 v[62:65], v[134:137], v[178:181], v[62:65]
	v_mfma_f32_16x16x32_bf16 v[58:61], v[142:145], v[178:181], v[58:61]
	v_mfma_f32_16x16x32_bf16 v[94:97], v[134:137], v[186:189], v[94:97]
	v_mfma_f32_16x16x32_bf16 v[82:85], v[142:145], v[186:189], v[82:85]
	v_mfma_f32_16x16x32_bf16 v[46:49], v[134:137], v[200:203], v[46:49]
	v_mfma_f32_16x16x32_bf16 v[26:29], v[142:145], v[200:203], v[26:29]
	v_mfma_f32_16x16x32_bf16 v[50:53], v[138:141], v[174:177], v[50:53]
	v_mfma_f32_16x16x32_bf16 v[30:33], v[146:149], v[174:177], v[30:33]
	v_mfma_f32_16x16x32_bf16 v[62:65], v[138:141], v[182:185], v[62:65]
	v_mfma_f32_16x16x32_bf16 v[58:61], v[146:149], v[182:185], v[58:61]
	v_mfma_f32_16x16x32_bf16 v[94:97], v[138:141], v[190:193], v[94:97]
	v_mfma_f32_16x16x32_bf16 v[82:85], v[146:149], v[190:193], v[82:85]
	v_mfma_f32_16x16x32_bf16 v[46:49], v[138:141], v[206:209], v[46:49]
	v_mfma_f32_16x16x32_bf16 v[26:29], v[146:149], v[206:209], v[26:29]
	s_setprio 0
	s_setprio 1
	v_mfma_f32_16x16x32_bf16 v[22:25], v[150:153], v[170:173], v[22:25]
	v_mfma_f32_16x16x32_bf16 v[10:13], v[158:161], v[170:173], v[10:13]
	v_mfma_f32_16x16x32_bf16 v[54:57], v[150:153], v[178:181], v[54:57]
	v_mfma_f32_16x16x32_bf16 v[66:69], v[158:161], v[178:181], v[66:69]
	v_mfma_f32_16x16x32_bf16 v[70:73], v[150:153], v[186:189], v[70:73]
	v_mfma_f32_16x16x32_bf16 v[42:45], v[158:161], v[186:189], v[42:45]
	v_mfma_f32_16x16x32_bf16 v[6:9], v[150:153], v[200:203], v[6:9]
	v_mfma_f32_16x16x32_bf16 v[2:5], v[158:161], v[200:203], v[2:5]
	v_mfma_f32_16x16x32_bf16 v[22:25], v[154:157], v[174:177], v[22:25]
	v_mfma_f32_16x16x32_bf16 v[10:13], v[166:169], v[174:177], v[10:13]
	v_mfma_f32_16x16x32_bf16 v[54:57], v[154:157], v[182:185], v[54:57]
	v_mfma_f32_16x16x32_bf16 v[66:69], v[166:169], v[182:185], v[66:69]
	v_mfma_f32_16x16x32_bf16 v[70:73], v[154:157], v[190:193], v[70:73]
	v_mfma_f32_16x16x32_bf16 v[42:45], v[166:169], v[190:193], v[42:45]
	v_mfma_f32_16x16x32_bf16 v[6:9], v[154:157], v[206:209], v[6:9]
	v_mfma_f32_16x16x32_bf16 v[2:5], v[166:169], v[206:209], v[2:5]
	s_setprio 0
	s_barrier
; #define PG8_STAGE(bufoff, gbase, voff) do { const int so_ = (int)(unsigned)((const char*)(gbase) - base_##voff); _Pragma("unroll") for (int _i = 0; _i < 2; ++_i) \
;         __builtin_amdgcn_raw_ptr_buffer_load_lds(rs_##voff, (PG8_LAS unsigned*)(lds + (bufoff) + ldsw + _i * 8192), 16, (int)(voff)[_i], so_, 0, 0); } while (0)
; #define PG8_LDA(dst, b, h) do { _Pragma("unroll") for (int m = 0; m < 4; ++m) _Pragma("unroll") for (int k = 0; k < 2; ++k) dst[m][k] = *(const PG8_LAS bf16x8*)(lds + PG8_SA(b, h) + aoff + m * 2048 + k * 1024); } while (0)
; #define PG8_LDB(dst, b, h) do { _Pragma("unroll") for (int n = 0; n < 2; ++n) _Pragma("unroll") for (int k = 0; k < 2; ++k) dst[n][k] = *(const PG8_LAS bf16x8*)(lds + PG8_SB(b, h) + boff + n * 2048 + k * 1024); } while (0)
; #define PG8_MMA(ai, bj, At, Bt) do { __builtin_amdgcn_s_setprio(1); _Pragma("unroll") for (int m = 0; m < 4; ++m) _Pragma("unroll") for (int n = 0; n < 2; ++n) _Pragma("unroll") for (int k = 0; k < 2; ++k) \
;         acc[ai][bj][m][n] = __builtin_amdgcn_mfma_f32_16x16x32_bf16(Bt[n][k], At[m][k], acc[ai][bj][m][n], 0, 0, 0); __builtin_amdgcn_s_setprio(0); } while (0)
; #define PG8_WAIT_V(n) asm volatile("s_waitcnt vmcnt(" #n ")" ::: "memory")
; #define PG8_WAIT_L(n) asm volatile("s_waitcnt lgkmcnt(" #n ")" ::: "memory")
; #define PG8_BAR __builtin_amdgcn_s_barrier()
; #define PG8_SCHED __builtin_amdgcn_sched_barrier(0)
; template <class Epi, class Sched, bool ALIGN_EPI = false, bool SP2 = false>
; __device__ __forceinline__ void gemm_phase(PG8_LAS unsigned char* lds, const Gemm g, const Sched& S, const Epi& E, int tid_in) {
;     ...
;             PG8_LDB(B0, 1, 0); PG8_LDB(B1, 1, 1); PG8_SCHED; PG8_LDA(At, 1, 0); PG8_STAGE(PG8_SA(0, 1), a2 + hstepA, voffA);
;             PG8_WAIT_V(8); PG8_WAIT_L(0); PG8_BAR; PG8_MMA(0, 0, At, B0); PG8_MMA(0, 1, At, B1); PG8_BAR; PG8_SCHED;
;             PG8_LDA(At, 1, 1); PG8_STAGE(PG8_SB(1, 0), b3, voffB); PG8_STAGE(PG8_SB(1, 1), b3 + hstepB, voffB); PG8_STAGE(PG8_SA(1, 0), a3, voffA);
;             PG8_WAIT_V(8); PG8_WAIT_L(0); PG8_BAR; PG8_MMA(1, 0, At, B0); PG8_MMA(1, 1, At, B1); PG8_BAR; PG8_SCHED;
	v_add_u32_e32 v133, 0x18000, v131
	ds_read_b128 v[134:137], v133
	ds_read_b128 v[138:141], v133 offset:1024
	ds_read_b128 v[142:145], v133 offset:2048
	ds_read_b128 v[146:149], v133 offset:3072
	v_add_u32_e32 v133, 0x1c000, v131
	ds_read_b128 v[150:153], v133
	ds_read_b128 v[154:157], v133 offset:1024
	ds_read_b128 v[158:161], v133 offset:2048
	ds_read_b128 v[166:169], v133 offset:3072
	s_add_i32 vcc_lo, s21, 0x80000
	s_mov_b32 m0, s66
	ds_read_b128 v[170:173], v132 offset:32768
	ds_read_b128 v[174:177], v132 offset:33792
	ds_read_b128 v[178:181], v132 offset:34816
	ds_read_b128 v[182:185], v132 offset:35840
	ds_read_b128 v[186:189], v132 offset:36864
	ds_read_b128 v[190:193], v132 offset:37888
	ds_read_b128 v[200:203], v132 offset:38912
	ds_read_b128 v[206:209], v132 offset:39936
	s_mov_b32 m0, s63
	s_nop 0
	buffer_load_dwordx4 v130, s[4:7], s21 offen lds
	s_mov_b32 m0, s66
	s_nop 0
	buffer_load_dwordx4 v0, s[4:7], vcc_lo offen lds
	s_mov_b32 m0, s67
	s_nop 0
	buffer_load_dwordx4 v130, s[4:7], vcc_lo offen lds
	s_waitcnt vmcnt(8)
	s_waitcnt lgkmcnt(0)
	s_barrier
	s_setprio 1
	s_waitcnt lgkmcnt(0)
	v_mfma_f32_16x16x32_bf16 v[34:37], v[134:137], v[170:173], v[34:37]
	v_mfma_f32_16x16x32_bf16 v[18:21], v[142:145], v[170:173], v[18:21]
	v_mfma_f32_16x16x32_bf16 v[86:89], v[134:137], v[178:181], v[86:89]
	v_mfma_f32_16x16x32_bf16 v[78:81], v[142:145], v[178:181], v[78:81]
	v_mfma_f32_16x16x32_bf16 v[106:109], v[134:137], v[186:189], v[106:109]
	v_mfma_f32_16x16x32_bf16 v[102:105], v[142:145], v[186:189], v[102:105]
	v_mfma_f32_16x16x32_bf16 v[126:129], v[134:137], v[200:203], v[126:129]
	v_mfma_f32_16x16x32_bf16 v[122:125], v[142:145], v[200:203], v[122:125]
	v_mfma_f32_16x16x32_bf16 v[34:37], v[138:141], v[174:177], v[34:37]
	v_mfma_f32_16x16x32_bf16 v[18:21], v[146:149], v[174:177], v[18:21]
	v_mfma_f32_16x16x32_bf16 v[86:89], v[138:141], v[182:185], v[86:89]
	v_mfma_f32_16x16x32_bf16 v[78:81], v[146:149], v[182:185], v[78:81]
	v_mfma_f32_16x16x32_bf16 v[106:109], v[138:141], v[190:193], v[106:109]
	v_mfma_f32_16x16x32_bf16 v[102:105], v[146:149], v[190:193], v[102:105]
	v_mfma_f32_16x16x32_bf16 v[126:129], v[138:141], v[206:209], v[126:129]
	v_mfma_f32_16x16x32_bf16 v[122:125], v[146:149], v[206:209], v[122:125]
	s_setprio 0
	s_setprio 1
	v_mfma_f32_16x16x32_bf16 v[14:17], v[150:153], v[170:173], v[14:17]
	v_mfma_f32_16x16x32_bf16 v[38:41], v[158:161], v[170:173], v[38:41]
	v_mfma_f32_16x16x32_bf16 v[74:77], v[150:153], v[178:181], v[74:77]
	v_mfma_f32_16x16x32_bf16 v[90:93], v[158:161], v[178:181], v[90:93]
	v_mfma_f32_16x16x32_bf16 v[98:101], v[150:153], v[186:189], v[98:101]
	v_mfma_f32_16x16x32_bf16 v[110:113], v[158:161], v[186:189], v[110:113]
	v_mfma_f32_16x16x32_bf16 v[118:121], v[150:153], v[200:203], v[118:121]
	v_mfma_f32_16x16x32_bf16 v[114:117], v[158:161], v[200:203], v[114:117]
	v_mfma_f32_16x16x32_bf16 v[14:17], v[154:157], v[174:177], v[14:17]
	v_mfma_f32_16x16x32_bf16 v[38:41], v[166:169], v[174:177], v[38:41]
	v_mfma_f32_16x16x32_bf16 v[74:77], v[154:157], v[182:185], v[74:77]
	v_mfma_f32_16x16x32_bf16 v[90:93], v[166:169], v[182:185], v[90:93]
	v_mfma_f32_16x16x32_bf16 v[98:101], v[154:157], v[190:193], v[98:101]
	v_mfma_f32_16x16x32_bf16 v[110:113], v[166:169], v[190:193], v[110:113]
	v_mfma_f32_16x16x32_bf16 v[118:121], v[154:157], v[206:209], v[118:121]
	v_mfma_f32_16x16x32_bf16 v[114:117], v[166:169], v[206:209], v[114:117]
	s_setprio 0
	s_barrier
	s_mov_b32 m0, s68
	s_add_i32 vcc_lo, s79, 0x80
	ds_read_b128 v[170:173], v132 offset:49152
	ds_read_b128 v[174:177], v132 offset:50176
	ds_read_b128 v[178:181], v132 offset:51200
	ds_read_b128 v[182:185], v132 offset:52224
	ds_read_b128 v[186:189], v132 offset:53248
	ds_read_b128 v[190:193], v132 offset:54272
	ds_read_b128 v[200:203], v132 offset:55296
	ds_read_b128 v[206:209], v132 offset:56320
	buffer_load_dwordx4 v0, s[40:43], vcc_lo offen lds
	s_mov_b32 m0, s69
	s_add_i32 s79, s79, 0x80080
	buffer_load_dwordx4 v130, s[40:43], vcc_lo offen lds
	s_mov_b32 m0, s73
	s_addk_i32 s21, 0x80
	buffer_load_dwordx4 v0, s[40:43], s79 offen lds
	s_mov_b32 m0, s74
	s_nop 0
	buffer_load_dwordx4 v130, s[40:43], s79 offen lds
	s_mov_b32 m0, s71
	s_nop 0
	buffer_load_dwordx4 v0, s[4:7], s21 offen lds
	s_waitcnt vmcnt(7)
	s_waitcnt lgkmcnt(0)
	s_barrier
; #define PG8_MMA(ai, bj, At, Bt) do { __builtin_amdgcn_s_setprio(1); _Pragma("unroll") for (int m = 0; m < 4; ++m) _Pragma("unroll") for (int n = 0; n < 2; ++n) _Pragma("unroll") for (int k = 0; k < 2; ++k) \
;         acc[ai][bj][m][n] = __builtin_amdgcn_mfma_f32_16x16x32_bf16(Bt[n][k], At[m][k], acc[ai][bj][m][n], 0, 0, 0); __builtin_amdgcn_s_setprio(0); } while (0)
; #define PG8_WAIT_V(n) asm volatile("s_waitcnt vmcnt(" #n ")" ::: "memory")
; #define PG8_WAIT_L(n) asm volatile("s_waitcnt lgkmcnt(" #n ")" ::: "memory")
; #define PG8_BAR __builtin_amdgcn_s_barrier()
; #define PG8_SCHED __builtin_amdgcn_sched_barrier(0)
; template <class Epi, class Sched, bool ALIGN_EPI = false, bool SP2 = false>
; __device__ __forceinline__ void gemm_phase(PG8_LAS unsigned char* lds, const Gemm g, const Sched& S, const Epi& E, int tid_in) {
;     ...
;             PG8_WAIT_V(8); PG8_WAIT_L(0); PG8_BAR; PG8_MMA(1, 0, At, B0); PG8_MMA(1, 1, At, B1); PG8_BAR; PG8_SCHED;
;     ...
;         if (zero_acc) {
; #pragma unroll
;         for (int a = 0; a < 2; ++a)
; #pragma unroll
;             for (int b = 0; b < 2; ++b)
; #pragma unroll
;                 for (int m = 0; m < 4; ++m)
; #pragma unroll
;                     for (int n = 0; n < 2; ++n) acc[a][b][m][n] = (f32x4){0.f, 0.f, 0.f, 0.f};
;         }
	s_setprio 1
	s_waitcnt lgkmcnt(0)
	v_mfma_f32_16x16x32_bf16 v[50:53], v[134:137], v[170:173], v[50:53]
	v_mfma_f32_16x16x32_bf16 v[30:33], v[142:145], v[170:173], v[30:33]
	v_mfma_f32_16x16x32_bf16 v[62:65], v[134:137], v[178:181], v[62:65]
	v_mfma_f32_16x16x32_bf16 v[58:61], v[142:145], v[178:181], v[58:61]
	v_mfma_f32_16x16x32_bf16 v[94:97], v[134:137], v[186:189], v[94:97]
	v_mfma_f32_16x16x32_bf16 v[82:85], v[142:145], v[186:189], v[82:85]
	v_mfma_f32_16x16x32_bf16 v[46:49], v[134:137], v[200:203], v[46:49]
	v_mfma_f32_16x16x32_bf16 v[26:29], v[142:145], v[200:203], v[26:29]
	v_mfma_f32_16x16x32_bf16 v[50:53], v[138:141], v[174:177], v[50:53]
	v_mfma_f32_16x16x32_bf16 v[30:33], v[146:149], v[174:177], v[30:33]
	v_mfma_f32_16x16x32_bf16 v[62:65], v[138:141], v[182:185], v[62:65]
	v_mfma_f32_16x16x32_bf16 v[58:61], v[146:149], v[182:185], v[58:61]
	v_mfma_f32_16x16x32_bf16 v[94:97], v[138:141], v[190:193], v[94:97]
	v_mfma_f32_16x16x32_bf16 v[82:85], v[146:149], v[190:193], v[82:85]
	v_mfma_f32_16x16x32_bf16 v[46:49], v[138:141], v[206:209], v[46:49]
	v_mfma_f32_16x16x32_bf16 v[26:29], v[146:149], v[206:209], v[26:29]
	s_setprio 0
	s_setprio 1
	v_mfma_f32_16x16x32_bf16 v[22:25], v[150:153], v[170:173], v[22:25]
	v_mfma_f32_16x16x32_bf16 v[10:13], v[158:161], v[170:173], v[10:13]
	v_mfma_f32_16x16x32_bf16 v[54:57], v[150:153], v[178:181], v[54:57]
	v_mfma_f32_16x16x32_bf16 v[66:69], v[158:161], v[178:181], v[66:69]
	v_mfma_f32_16x16x32_bf16 v[70:73], v[150:153], v[186:189], v[70:73]
	v_mfma_f32_16x16x32_bf16 v[42:45], v[158:161], v[186:189], v[42:45]
	v_mfma_f32_16x16x32_bf16 v[6:9], v[150:153], v[200:203], v[6:9]
	v_mfma_f32_16x16x32_bf16 v[2:5], v[158:161], v[200:203], v[2:5]
	v_mfma_f32_16x16x32_bf16 v[22:25], v[154:157], v[174:177], v[22:25]
	v_mfma_f32_16x16x32_bf16 v[10:13], v[166:169], v[174:177], v[10:13]
	v_mfma_f32_16x16x32_bf16 v[54:57], v[154:157], v[182:185], v[54:57]
	v_mfma_f32_16x16x32_bf16 v[66:69], v[166:169], v[182:185], v[66:69]
	v_mfma_f32_16x16x32_bf16 v[70:73], v[154:157], v[190:193], v[70:73]
	v_mfma_f32_16x16x32_bf16 v[42:45], v[166:169], v[190:193], v[42:45]
	v_mfma_f32_16x16x32_bf16 v[6:9], v[154:157], v[206:209], v[6:9]
	v_mfma_f32_16x16x32_bf16 v[2:5], v[166:169], v[206:209], v[2:5]
	s_setprio 0
	s_barrier
	s_add_i32 s19, s19, 2
	s_add_u32 s44, s44, 0x100
	s_addc_u32 s45, s45, 0
	s_cmp_gt_u32 s19, 29
	s_cbranch_scc0 .LBB0_1265
	s_andn2_b64 vcc, exec, s[38:39]
	s_cbranch_vccnz .LBB0_1257
	v_mov_b32_e32 v2, 0
	s_mov_b64 s[12:13], s[24:25]
	s_mov_b32 s10, s16
	s_mov_b32 s48, s20
	s_mov_b64 s[14:15], s[22:23]
	s_mov_b32 s13, s78
	v_mov_b32_e32 v3, v2
	v_mov_b32_e32 v4, v2
	v_mov_b32_e32 v5, v2
	v_mov_b32_e32 v6, v2
	v_mov_b32_e32 v7, v2
	v_mov_b32_e32 v8, v2
	v_mov_b32_e32 v9, v2
	v_mov_b32_e32 v42, v2
	v_mov_b32_e32 v43, v2
	v_mov_b32_e32 v44, v2
	v_mov_b32_e32 v45, v2
	v_mov_b32_e32 v70, v2
	v_mov_b32_e32 v71, v2
	v_mov_b32_e32 v72, v2
	v_mov_b32_e32 v73, v2
	v_mov_b32_e32 v66, v2
	v_mov_b32_e32 v67, v2
	v_mov_b32_e32 v68, v2
	v_mov_b32_e32 v69, v2
	v_mov_b32_e32 v54, v2
	v_mov_b32_e32 v55, v2
	v_mov_b32_e32 v56, v2
	v_mov_b32_e32 v57, v2
	v_mov_b32_e32 v10, v2
	v_mov_b32_e32 v11, v2
	v_mov_b32_e32 v12, v2
	v_mov_b32_e32 v13, v2
	v_mov_b32_e32 v22, v2
	v_mov_b32_e32 v23, v2
	v_mov_b32_e32 v24, v2
	v_mov_b32_e32 v25, v2
	v_mov_b32_e32 v26, v2
	v_mov_b32_e32 v27, v2
	v_mov_b32_e32 v28, v2
	v_mov_b32_e32 v29, v2
	v_mov_b32_e32 v46, v2
	v_mov_b32_e32 v47, v2
	v_mov_b32_e32 v48, v2
	v_mov_b32_e32 v49, v2
	v_mov_b32_e32 v82, v2
	v_mov_b32_e32 v83, v2
	v_mov_b32_e32 v84, v2
	v_mov_b32_e32 v85, v2
	v_mov_b32_e32 v94, v2
	v_mov_b32_e32 v95, v2
	v_mov_b32_e32 v96, v2
	v_mov_b32_e32 v97, v2
	v_mov_b32_e32 v58, v2
	v_mov_b32_e32 v59, v2
	v_mov_b32_e32 v60, v2
	v_mov_b32_e32 v61, v2
	v_mov_b32_e32 v62, v2
	v_mov_b32_e32 v63, v2
	v_mov_b32_e32 v64, v2
	v_mov_b32_e32 v65, v2
	v_mov_b32_e32 v30, v2
	v_mov_b32_e32 v31, v2
	v_mov_b32_e32 v32, v2
	v_mov_b32_e32 v33, v2
	v_mov_b32_e32 v50, v2
	v_mov_b32_e32 v51, v2
	v_mov_b32_e32 v52, v2
	v_mov_b32_e32 v53, v2
	v_mov_b32_e32 v114, v2
	v_mov_b32_e32 v115, v2
	v_mov_b32_e32 v116, v2
	v_mov_b32_e32 v117, v2
	v_mov_b32_e32 v118, v2
	v_mov_b32_e32 v119, v2
	v_mov_b32_e32 v120, v2
	v_mov_b32_e32 v121, v2
	v_mov_b32_e32 v110, v2
	v_mov_b32_e32 v111, v2
	v_mov_b32_e32 v112, v2
	v_mov_b32_e32 v113, v2
	v_mov_b32_e32 v98, v2
	v_mov_b32_e32 v99, v2
	v_mov_b32_e32 v100, v2
	v_mov_b32_e32 v101, v2
	v_mov_b32_e32 v90, v2
	v_mov_b32_e32 v91, v2
	v_mov_b32_e32 v92, v2
	v_mov_b32_e32 v93, v2
	v_mov_b32_e32 v74, v2
	v_mov_b32_e32 v75, v2
	v_mov_b32_e32 v76, v2
	v_mov_b32_e32 v77, v2
	v_mov_b32_e32 v38, v2
	v_mov_b32_e32 v39, v2
	v_mov_b32_e32 v40, v2
	v_mov_b32_e32 v41, v2
	v_mov_b32_e32 v14, v2
	v_mov_b32_e32 v15, v2
	v_mov_b32_e32 v16, v2
	v_mov_b32_e32 v17, v2
	v_mov_b32_e32 v122, v2
	v_mov_b32_e32 v123, v2
	v_mov_b32_e32 v124, v2
	v_mov_b32_e32 v125, v2
	v_mov_b32_e32 v126, v2
	v_mov_b32_e32 v127, v2
	v_mov_b32_e32 v128, v2
	v_mov_b32_e32 v129, v2
	v_mov_b32_e32 v102, v2
	v_mov_b32_e32 v103, v2
	v_mov_b32_e32 v104, v2
	v_mov_b32_e32 v105, v2
	v_mov_b32_e32 v106, v2
	v_mov_b32_e32 v107, v2
	v_mov_b32_e32 v108, v2
	v_mov_b32_e32 v109, v2
	v_mov_b32_e32 v78, v2
	v_mov_b32_e32 v79, v2
	v_mov_b32_e32 v80, v2
	v_mov_b32_e32 v81, v2
	v_mov_b32_e32 v86, v2
	v_mov_b32_e32 v87, v2
	v_mov_b32_e32 v88, v2
	v_mov_b32_e32 v89, v2
	v_mov_b32_e32 v18, v2
	v_mov_b32_e32 v19, v2
	v_mov_b32_e32 v20, v2
	v_mov_b32_e32 v21, v2
	v_mov_b32_e32 v34, v2
	v_mov_b32_e32 v35, v2
	v_mov_b32_e32 v36, v2
	v_mov_b32_e32 v37, v2
	s_branch .LBB0_1257

; #define PG8_STAGE(bufoff, gbase, voff) do { const int so_ = (int)(unsigned)((const char*)(gbase) - base_##voff); _Pragma("unroll") for (int _i = 0; _i < 2; ++_i) \
;         __builtin_amdgcn_raw_ptr_buffer_load_lds(rs_##voff, (PG8_LAS unsigned*)(lds + (bufoff) + ldsw + _i * 8192), 16, (int)(voff)[_i], so_, 0, 0); } while (0)
; #define PG8_LDA(dst, b, h) do { _Pragma("unroll") for (int m = 0; m < 4; ++m) _Pragma("unroll") for (int k = 0; k < 2; ++k) dst[m][k] = *(const PG8_LAS bf16x8*)(lds + PG8_SA(b, h) + aoff + m * 2048 + k * 1024); } while (0)
; #define PG8_LDB(dst, b, h) do { _Pragma("unroll") for (int n = 0; n < 2; ++n) _Pragma("unroll") for (int k = 0; k < 2; ++k) dst[n][k] = *(const PG8_LAS bf16x8*)(lds + PG8_SB(b, h) + boff + n * 2048 + k * 1024); } while (0)
; #define PG8_MMA(ai, bj, At, Bt) do { __builtin_amdgcn_s_setprio(1); _Pragma("unroll") for (int m = 0; m < 4; ++m) _Pragma("unroll") for (int n = 0; n < 2; ++n) _Pragma("unroll") for (int k = 0; k < 2; ++k) \
;         acc[ai][bj][m][n] = __builtin_amdgcn_mfma_f32_16x16x32_bf16(Bt[n][k], At[m][k], acc[ai][bj][m][n], 0, 0, 0); __builtin_amdgcn_s_setprio(0); } while (0)
; #define PG8_WAIT_V(n) asm volatile("s_waitcnt vmcnt(" #n ")" ::: "memory")
; #define PG8_WAIT_L(n) asm volatile("s_waitcnt lgkmcnt(" #n ")" ::: "memory")
; #define PG8_BAR __builtin_amdgcn_s_barrier()
; #define PG8_SCHED __builtin_amdgcn_sched_barrier(0)
; template <class Epi, class Sched, bool ALIGN_EPI = false, bool SP2 = false>
; __device__ __forceinline__ void gemm_phase(PG8_LAS unsigned char* lds, const Gemm g, const Sched& S, const Epi& E, int tid_in) {
;     ...
;             PG8_LDB(B0, 0, 0); PG8_LDB(B1, 0, 1); PG8_SCHED; PG8_LDA(At, 0, 0); PG8_STAGE(PG8_SA(1, 1), a1 + hstepA, voffA);
;             PG8_WAIT_V(8); PG8_WAIT_L(0); PG8_BAR; PG8_MMA(0, 0, At, B0); PG8_MMA(0, 1, At, B1); PG8_BAR; PG8_SCHED;
;             PG8_LDA(At, 0, 1); PG8_STAGE(PG8_SB(0, 0), b2, voffB); PG8_STAGE(PG8_SB(0, 1), b2 + hstepB, voffB); PG8_STAGE(PG8_SA(0, 0), a2, voffA);
;             PG8_WAIT_V(8); PG8_WAIT_L(0); PG8_BAR; PG8_MMA(1, 0, At, B0); PG8_MMA(1, 1, At, B1); PG8_BAR; PG8_SCHED;
.LBB0_1514:
	v_add_u32_e32 v141, 0x10000, v139
	ds_read_b128 v[130:133], v141
	ds_read_b128 v[142:145], v141 offset:1024
	ds_read_b128 v[146:149], v141 offset:2048
	ds_read_b128 v[150:153], v141 offset:3072
	v_add_u32_e32 v141, 0x14000, v139
	ds_read_b128 v[154:157], v141
	ds_read_b128 v[158:161], v141 offset:1024
	ds_read_b128 v[162:165], v141 offset:2048
	ds_read_b128 v[166:169], v141 offset:3072
	s_add_u32 s38, s16, 0x100
	s_addc_u32 s39, s17, 0
	s_sub_i32 s16, s16, s4
	s_add_i32 s16, s16, 0x80080
	s_sub_i32 s74, s16, 0x80000
	s_cmp_eq_u32 s73, 28
	s_cselect_b32 s17, s18, s38
	s_mov_b32 m0, s67
	ds_read_b128 v[170:173], v140
	ds_read_b128 v[174:177], v140 offset:1024
	ds_read_b128 v[178:181], v140 offset:2048
	ds_read_b128 v[182:185], v140 offset:3072
	ds_read_b128 v[186:189], v140 offset:4096
	ds_read_b128 v[190:193], v140 offset:5120
	ds_read_b128 v[200:203], v140 offset:6144
	ds_read_b128 v[206:209], v140 offset:7168
	s_mov_b32 m0, s62
	s_nop 0
	buffer_load_dwordx4 v135, s[4:7], s74 offen lds
	s_mov_b32 m0, s67
	s_nop 0
	buffer_load_dwordx4 v0, s[4:7], s16 offen lds
	s_mov_b32 m0, s68
	s_nop 0
	buffer_load_dwordx4 v135, s[4:7], s16 offen lds
	s_waitcnt vmcnt(8)
	s_waitcnt lgkmcnt(0)
	s_barrier
	s_setprio 1
	s_waitcnt lgkmcnt(0)
	v_mfma_f32_16x16x32_bf16 v[126:129], v[130:133], v[170:173], v[126:129]
	v_mfma_f32_16x16x32_bf16 v[122:125], v[146:149], v[170:173], v[122:125]
	v_mfma_f32_16x16x32_bf16 v[110:113], v[130:133], v[178:181], v[110:113]
	v_mfma_f32_16x16x32_bf16 v[106:109], v[146:149], v[178:181], v[106:109]
	v_mfma_f32_16x16x32_bf16 v[94:97], v[130:133], v[186:189], v[94:97]
	v_mfma_f32_16x16x32_bf16 v[90:93], v[146:149], v[186:189], v[90:93]
	v_mfma_f32_16x16x32_bf16 v[78:81], v[130:133], v[200:203], v[78:81]
	v_mfma_f32_16x16x32_bf16 v[74:77], v[146:149], v[200:203], v[74:77]
	v_mfma_f32_16x16x32_bf16 v[126:129], v[142:145], v[174:177], v[126:129]
	v_mfma_f32_16x16x32_bf16 v[122:125], v[150:153], v[174:177], v[122:125]
	v_mfma_f32_16x16x32_bf16 v[110:113], v[142:145], v[182:185], v[110:113]
	v_mfma_f32_16x16x32_bf16 v[106:109], v[150:153], v[182:185], v[106:109]
	v_mfma_f32_16x16x32_bf16 v[94:97], v[142:145], v[190:193], v[94:97]
	v_mfma_f32_16x16x32_bf16 v[90:93], v[150:153], v[190:193], v[90:93]
	v_mfma_f32_16x16x32_bf16 v[78:81], v[142:145], v[206:209], v[78:81]
	v_mfma_f32_16x16x32_bf16 v[74:77], v[150:153], v[206:209], v[74:77]
	s_setprio 0
	s_setprio 1
	v_mfma_f32_16x16x32_bf16 v[118:121], v[154:157], v[170:173], v[118:121]
	v_mfma_f32_16x16x32_bf16 v[114:117], v[162:165], v[170:173], v[114:117]
	v_mfma_f32_16x16x32_bf16 v[102:105], v[154:157], v[178:181], v[102:105]
	v_mfma_f32_16x16x32_bf16 v[98:101], v[162:165], v[178:181], v[98:101]
	v_mfma_f32_16x16x32_bf16 v[86:89], v[154:157], v[186:189], v[86:89]
	v_mfma_f32_16x16x32_bf16 v[82:85], v[162:165], v[186:189], v[82:85]
	v_mfma_f32_16x16x32_bf16 v[70:73], v[154:157], v[200:203], v[70:73]
	v_mfma_f32_16x16x32_bf16 v[66:69], v[162:165], v[200:203], v[66:69]
	v_mfma_f32_16x16x32_bf16 v[118:121], v[158:161], v[174:177], v[118:121]
	v_mfma_f32_16x16x32_bf16 v[114:117], v[166:169], v[174:177], v[114:117]
	v_mfma_f32_16x16x32_bf16 v[102:105], v[158:161], v[182:185], v[102:105]
	v_mfma_f32_16x16x32_bf16 v[98:101], v[166:169], v[182:185], v[98:101]
	v_mfma_f32_16x16x32_bf16 v[86:89], v[158:161], v[190:193], v[86:89]
	v_mfma_f32_16x16x32_bf16 v[82:85], v[166:169], v[190:193], v[82:85]
	v_mfma_f32_16x16x32_bf16 v[70:73], v[158:161], v[206:209], v[70:73]
	v_mfma_f32_16x16x32_bf16 v[66:69], v[166:169], v[206:209], v[66:69]
	s_setprio 0
	s_barrier
	s_cselect_b32 s16, s15, s19
	s_mov_b32 m0, s35
	s_mov_b32 s42, s6
	s_mov_b32 s43, s7
	s_sub_i32 s16, s16, s40
	ds_read_b128 v[170:173], v140 offset:16384
	ds_read_b128 v[174:177], v140 offset:17408
	ds_read_b128 v[178:181], v140 offset:18432
	ds_read_b128 v[182:185], v140 offset:19456
	ds_read_b128 v[186:189], v140 offset:20480
	ds_read_b128 v[190:193], v140 offset:21504
	ds_read_b128 v[200:203], v140 offset:22528
	ds_read_b128 v[206:209], v140 offset:23552
	buffer_load_dwordx4 v134, s[40:43], s16 offen lds
	s_mov_b32 m0, s44
	s_add_i32 s74, s16, 0x80000
	buffer_load_dwordx4 v136, s[40:43], s16 offen lds
	s_mov_b32 m0, s45
	s_sub_i32 s17, s17, s4
	buffer_load_dwordx4 v134, s[40:43], s74 offen lds
	s_mov_b32 m0, s46
	s_nop 0
	buffer_load_dwordx4 v136, s[40:43], s74 offen lds
	s_mov_b32 m0, s34
	s_nop 0
	buffer_load_dwordx4 v0, s[4:7], s17 offen lds
	s_waitcnt vmcnt(7)
	s_waitcnt lgkmcnt(0)
	s_barrier
	s_setprio 1
	s_waitcnt lgkmcnt(0)
	v_mfma_f32_16x16x32_bf16 v[62:65], v[130:133], v[170:173], v[62:65]
	v_mfma_f32_16x16x32_bf16 v[58:61], v[146:149], v[170:173], v[58:61]
	v_mfma_f32_16x16x32_bf16 v[46:49], v[130:133], v[178:181], v[46:49]
	v_mfma_f32_16x16x32_bf16 v[42:45], v[146:149], v[178:181], v[42:45]
	v_mfma_f32_16x16x32_bf16 v[30:33], v[130:133], v[186:189], v[30:33]
	v_mfma_f32_16x16x32_bf16 v[26:29], v[146:149], v[186:189], v[26:29]
	v_mfma_f32_16x16x32_bf16 v[14:17], v[130:133], v[200:203], v[14:17]
	v_mfma_f32_16x16x32_bf16 v[10:13], v[146:149], v[200:203], v[10:13]
	v_mfma_f32_16x16x32_bf16 v[62:65], v[142:145], v[174:177], v[62:65]
	v_mfma_f32_16x16x32_bf16 v[58:61], v[150:153], v[174:177], v[58:61]
	v_mfma_f32_16x16x32_bf16 v[46:49], v[142:145], v[182:185], v[46:49]
	v_mfma_f32_16x16x32_bf16 v[42:45], v[150:153], v[182:185], v[42:45]
	v_mfma_f32_16x16x32_bf16 v[30:33], v[142:145], v[190:193], v[30:33]
	v_mfma_f32_16x16x32_bf16 v[26:29], v[150:153], v[190:193], v[26:29]
	v_mfma_f32_16x16x32_bf16 v[14:17], v[142:145], v[206:209], v[14:17]
	v_mfma_f32_16x16x32_bf16 v[10:13], v[150:153], v[206:209], v[10:13]
	s_setprio 0
	s_setprio 1
	v_mfma_f32_16x16x32_bf16 v[54:57], v[154:157], v[170:173], v[54:57]
	v_mfma_f32_16x16x32_bf16 v[50:53], v[162:165], v[170:173], v[50:53]
	v_mfma_f32_16x16x32_bf16 v[38:41], v[154:157], v[178:181], v[38:41]
	v_mfma_f32_16x16x32_bf16 v[34:37], v[162:165], v[178:181], v[34:37]
	v_mfma_f32_16x16x32_bf16 v[22:25], v[154:157], v[186:189], v[22:25]
	v_mfma_f32_16x16x32_bf16 v[18:21], v[162:165], v[186:189], v[18:21]
	v_mfma_f32_16x16x32_bf16 v[6:9], v[154:157], v[200:203], v[6:9]
	v_mfma_f32_16x16x32_bf16 v[2:5], v[162:165], v[200:203], v[2:5]
	v_mfma_f32_16x16x32_bf16 v[54:57], v[158:161], v[174:177], v[54:57]
	v_mfma_f32_16x16x32_bf16 v[50:53], v[166:169], v[174:177], v[50:53]
	v_mfma_f32_16x16x32_bf16 v[38:41], v[158:161], v[182:185], v[38:41]
	v_mfma_f32_16x16x32_bf16 v[34:37], v[166:169], v[182:185], v[34:37]
	v_mfma_f32_16x16x32_bf16 v[22:25], v[158:161], v[190:193], v[22:25]
	v_mfma_f32_16x16x32_bf16 v[18:21], v[166:169], v[190:193], v[18:21]
	v_mfma_f32_16x16x32_bf16 v[6:9], v[158:161], v[206:209], v[6:9]
	v_mfma_f32_16x16x32_bf16 v[2:5], v[166:169], v[206:209], v[2:5]
	s_setprio 0
	s_barrier
; #define PG8_STAGE(bufoff, gbase, voff) do { const int so_ = (int)(unsigned)((const char*)(gbase) - base_##voff); _Pragma("unroll") for (int _i = 0; _i < 2; ++_i) \
;         __builtin_amdgcn_raw_ptr_buffer_load_lds(rs_##voff, (PG8_LAS unsigned*)(lds + (bufoff) + ldsw + _i * 8192), 16, (int)(voff)[_i], so_, 0, 0); } while (0)
; #define PG8_LDA(dst, b, h) do { _Pragma("unroll") for (int m = 0; m < 4; ++m) _Pragma("unroll") for (int k = 0; k < 2; ++k) dst[m][k] = *(const PG8_LAS bf16x8*)(lds + PG8_SA(b, h) + aoff + m * 2048 + k * 1024); } while (0)
; #define PG8_LDB(dst, b, h) do { _Pragma("unroll") for (int n = 0; n < 2; ++n) _Pragma("unroll") for (int k = 0; k < 2; ++k) dst[n][k] = *(const PG8_LAS bf16x8*)(lds + PG8_SB(b, h) + boff + n * 2048 + k * 1024); } while (0)
; #define PG8_MMA(ai, bj, At, Bt) do { __builtin_amdgcn_s_setprio(1); _Pragma("unroll") for (int m = 0; m < 4; ++m) _Pragma("unroll") for (int n = 0; n < 2; ++n) _Pragma("unroll") for (int k = 0; k < 2; ++k) \
;         acc[ai][bj][m][n] = __builtin_amdgcn_mfma_f32_16x16x32_bf16(Bt[n][k], At[m][k], acc[ai][bj][m][n], 0, 0, 0); __builtin_amdgcn_s_setprio(0); } while (0)
; #define PG8_WAIT_V(n) asm volatile("s_waitcnt vmcnt(" #n ")" ::: "memory")
; #define PG8_WAIT_L(n) asm volatile("s_waitcnt lgkmcnt(" #n ")" ::: "memory")
; #define PG8_BAR __builtin_amdgcn_s_barrier()
; #define PG8_SCHED __builtin_amdgcn_sched_barrier(0)
; template <class Epi, class Sched, bool ALIGN_EPI = false, bool SP2 = false>
; __device__ __forceinline__ void gemm_phase(PG8_LAS unsigned char* lds, const Gemm g, const Sched& S, const Epi& E, int tid_in) {
;     ...
;             PG8_LDB(B0, 1, 0); PG8_LDB(B1, 1, 1); PG8_SCHED; PG8_LDA(At, 1, 0); PG8_STAGE(PG8_SA(0, 1), a2 + hstepA, voffA);
;             PG8_WAIT_V(8); PG8_WAIT_L(0); PG8_BAR; PG8_MMA(0, 0, At, B0); PG8_MMA(0, 1, At, B1); PG8_BAR; PG8_SCHED;
;             PG8_LDA(At, 1, 1); PG8_STAGE(PG8_SB(1, 0), b3, voffB); PG8_STAGE(PG8_SB(1, 1), b3 + hstepB, voffB); PG8_STAGE(PG8_SA(1, 0), a3, voffA);
;             PG8_WAIT_V(8); PG8_WAIT_L(0); PG8_BAR; PG8_MMA(1, 0, At, B0); PG8_MMA(1, 1, At, B1); PG8_BAR; PG8_SCHED;
	v_add_u32_e32 v141, 0x18000, v139
	ds_read_b128 v[130:133], v141
	ds_read_b128 v[142:145], v141 offset:1024
	ds_read_b128 v[146:149], v141 offset:2048
	ds_read_b128 v[150:153], v141 offset:3072
	v_add_u32_e32 v141, 0x1c000, v139
	ds_read_b128 v[154:157], v141
	ds_read_b128 v[158:161], v141 offset:1024
	ds_read_b128 v[162:165], v141 offset:2048
	ds_read_b128 v[166:169], v141 offset:3072
	s_add_i32 s74, s17, 0x80000
	s_mov_b32 m0, s48
	ds_read_b128 v[170:173], v140 offset:32768
	ds_read_b128 v[174:177], v140 offset:33792
	ds_read_b128 v[178:181], v140 offset:34816
	ds_read_b128 v[182:185], v140 offset:35840
	ds_read_b128 v[186:189], v140 offset:36864
	ds_read_b128 v[190:193], v140 offset:37888
	ds_read_b128 v[200:203], v140 offset:38912
	ds_read_b128 v[206:209], v140 offset:39936
	s_mov_b32 m0, s47
	s_nop 0
	buffer_load_dwordx4 v135, s[4:7], s17 offen lds
	s_mov_b32 m0, s48
	s_nop 0
	buffer_load_dwordx4 v0, s[4:7], s74 offen lds
	s_mov_b32 m0, s49
	s_nop 0
	buffer_load_dwordx4 v135, s[4:7], s74 offen lds
	s_waitcnt vmcnt(8)
	s_waitcnt lgkmcnt(0)
	s_barrier
	s_setprio 1
	s_waitcnt lgkmcnt(0)
	v_mfma_f32_16x16x32_bf16 v[126:129], v[130:133], v[170:173], v[126:129]
	v_mfma_f32_16x16x32_bf16 v[122:125], v[146:149], v[170:173], v[122:125]
	v_mfma_f32_16x16x32_bf16 v[110:113], v[130:133], v[178:181], v[110:113]
	v_mfma_f32_16x16x32_bf16 v[106:109], v[146:149], v[178:181], v[106:109]
	v_mfma_f32_16x16x32_bf16 v[94:97], v[130:133], v[186:189], v[94:97]
	v_mfma_f32_16x16x32_bf16 v[90:93], v[146:149], v[186:189], v[90:93]
	v_mfma_f32_16x16x32_bf16 v[78:81], v[130:133], v[200:203], v[78:81]
	v_mfma_f32_16x16x32_bf16 v[74:77], v[146:149], v[200:203], v[74:77]
	v_mfma_f32_16x16x32_bf16 v[126:129], v[142:145], v[174:177], v[126:129]
	v_mfma_f32_16x16x32_bf16 v[122:125], v[150:153], v[174:177], v[122:125]
	v_mfma_f32_16x16x32_bf16 v[110:113], v[142:145], v[182:185], v[110:113]
	v_mfma_f32_16x16x32_bf16 v[106:109], v[150:153], v[182:185], v[106:109]
	v_mfma_f32_16x16x32_bf16 v[94:97], v[142:145], v[190:193], v[94:97]
	v_mfma_f32_16x16x32_bf16 v[90:93], v[150:153], v[190:193], v[90:93]
	v_mfma_f32_16x16x32_bf16 v[78:81], v[142:145], v[206:209], v[78:81]
	v_mfma_f32_16x16x32_bf16 v[74:77], v[150:153], v[206:209], v[74:77]
	s_setprio 0
	s_setprio 1
	v_mfma_f32_16x16x32_bf16 v[118:121], v[154:157], v[170:173], v[118:121]
	v_mfma_f32_16x16x32_bf16 v[114:117], v[162:165], v[170:173], v[114:117]
	v_mfma_f32_16x16x32_bf16 v[102:105], v[154:157], v[178:181], v[102:105]
	v_mfma_f32_16x16x32_bf16 v[98:101], v[162:165], v[178:181], v[98:101]
	v_mfma_f32_16x16x32_bf16 v[86:89], v[154:157], v[186:189], v[86:89]
	v_mfma_f32_16x16x32_bf16 v[82:85], v[162:165], v[186:189], v[82:85]
	v_mfma_f32_16x16x32_bf16 v[70:73], v[154:157], v[200:203], v[70:73]
	v_mfma_f32_16x16x32_bf16 v[66:69], v[162:165], v[200:203], v[66:69]
	v_mfma_f32_16x16x32_bf16 v[118:121], v[158:161], v[174:177], v[118:121]
	v_mfma_f32_16x16x32_bf16 v[114:117], v[166:169], v[174:177], v[114:117]
	v_mfma_f32_16x16x32_bf16 v[102:105], v[158:161], v[182:185], v[102:105]
	v_mfma_f32_16x16x32_bf16 v[98:101], v[166:169], v[182:185], v[98:101]
	v_mfma_f32_16x16x32_bf16 v[86:89], v[158:161], v[190:193], v[86:89]
	v_mfma_f32_16x16x32_bf16 v[82:85], v[166:169], v[190:193], v[82:85]
	v_mfma_f32_16x16x32_bf16 v[70:73], v[158:161], v[206:209], v[70:73]
	v_mfma_f32_16x16x32_bf16 v[66:69], v[166:169], v[206:209], v[66:69]
	s_setprio 0
	s_barrier
	s_mov_b32 m0, s53
	s_add_i32 s74, s16, 0x80
	ds_read_b128 v[170:173], v140 offset:49152
	ds_read_b128 v[174:177], v140 offset:50176
	ds_read_b128 v[178:181], v140 offset:51200
	ds_read_b128 v[182:185], v140 offset:52224
	ds_read_b128 v[186:189], v140 offset:53248
	ds_read_b128 v[190:193], v140 offset:54272
	ds_read_b128 v[200:203], v140 offset:55296
	ds_read_b128 v[206:209], v140 offset:56320
	buffer_load_dwordx4 v134, s[40:43], s74 offen lds
	s_mov_b32 m0, s60
	s_add_i32 s16, s16, 0x80080
	buffer_load_dwordx4 v136, s[40:43], s74 offen lds
	s_mov_b32 m0, s63
	s_addk_i32 s17, 0x80
	buffer_load_dwordx4 v134, s[40:43], s16 offen lds
	s_mov_b32 m0, s66
	s_nop 0
	buffer_load_dwordx4 v136, s[40:43], s16 offen lds
	s_mov_b32 m0, s61
	s_nop 0
	buffer_load_dwordx4 v0, s[4:7], s17 offen lds
	s_waitcnt vmcnt(7)
	s_waitcnt lgkmcnt(0)
	s_barrier
	s_setprio 1
	s_waitcnt lgkmcnt(0)
	v_mfma_f32_16x16x32_bf16 v[62:65], v[130:133], v[170:173], v[62:65]
	v_mfma_f32_16x16x32_bf16 v[58:61], v[146:149], v[170:173], v[58:61]
	v_mfma_f32_16x16x32_bf16 v[46:49], v[130:133], v[178:181], v[46:49]
	v_mfma_f32_16x16x32_bf16 v[42:45], v[146:149], v[178:181], v[42:45]
	v_mfma_f32_16x16x32_bf16 v[30:33], v[130:133], v[186:189], v[30:33]
	v_mfma_f32_16x16x32_bf16 v[26:29], v[146:149], v[186:189], v[26:29]
	v_mfma_f32_16x16x32_bf16 v[14:17], v[130:133], v[200:203], v[14:17]
	v_mfma_f32_16x16x32_bf16 v[10:13], v[146:149], v[200:203], v[10:13]
	v_mfma_f32_16x16x32_bf16 v[62:65], v[142:145], v[174:177], v[62:65]
	v_mfma_f32_16x16x32_bf16 v[58:61], v[150:153], v[174:177], v[58:61]
	v_mfma_f32_16x16x32_bf16 v[46:49], v[142:145], v[182:185], v[46:49]
	v_mfma_f32_16x16x32_bf16 v[42:45], v[150:153], v[182:185], v[42:45]
	v_mfma_f32_16x16x32_bf16 v[30:33], v[142:145], v[190:193], v[30:33]
	v_mfma_f32_16x16x32_bf16 v[26:29], v[150:153], v[190:193], v[26:29]
	v_mfma_f32_16x16x32_bf16 v[14:17], v[142:145], v[206:209], v[14:17]
	v_mfma_f32_16x16x32_bf16 v[10:13], v[150:153], v[206:209], v[10:13]
	s_setprio 0
	s_setprio 1
	v_mfma_f32_16x16x32_bf16 v[54:57], v[154:157], v[170:173], v[54:57]
	v_mfma_f32_16x16x32_bf16 v[50:53], v[162:165], v[170:173], v[50:53]
	v_mfma_f32_16x16x32_bf16 v[38:41], v[154:157], v[178:181], v[38:41]
	v_mfma_f32_16x16x32_bf16 v[34:37], v[162:165], v[178:181], v[34:37]
	v_mfma_f32_16x16x32_bf16 v[22:25], v[154:157], v[186:189], v[22:25]
	v_mfma_f32_16x16x32_bf16 v[18:21], v[162:165], v[186:189], v[18:21]
	v_mfma_f32_16x16x32_bf16 v[6:9], v[154:157], v[200:203], v[6:9]
	v_mfma_f32_16x16x32_bf16 v[2:5], v[162:165], v[200:203], v[2:5]
	v_mfma_f32_16x16x32_bf16 v[54:57], v[158:161], v[174:177], v[54:57]
	v_mfma_f32_16x16x32_bf16 v[50:53], v[166:169], v[174:177], v[50:53]
	v_mfma_f32_16x16x32_bf16 v[38:41], v[158:161], v[182:185], v[38:41]
	v_mfma_f32_16x16x32_bf16 v[34:37], v[166:169], v[182:185], v[34:37]
	v_mfma_f32_16x16x32_bf16 v[22:25], v[158:161], v[190:193], v[22:25]
	v_mfma_f32_16x16x32_bf16 v[18:21], v[166:169], v[190:193], v[18:21]
	v_mfma_f32_16x16x32_bf16 v[6:9], v[158:161], v[206:209], v[6:9]
	v_mfma_f32_16x16x32_bf16 v[2:5], v[166:169], v[206:209], v[2:5]
	s_setprio 0
	s_barrier
	s_add_i32 s73, s73, 2
	s_add_u32 s19, s19, 0x100
	s_addc_u32 s21, s21, 0
	s_cmp_gt_u32 s73, 29
	s_mov_b64 s[16:17], s[38:39]
	s_cbranch_scc0 .LBB0_1514
	s_and_b64 vcc, exec, s[12:13]
	s_cbranch_vccz .LBB0_1517
	s_barrier

; #define PG8_STAGE(bufoff, gbase, voff) do { const int so_ = (int)(unsigned)((const char*)(gbase) - base_##voff); _Pragma("unroll") for (int _i = 0; _i < 2; ++_i) \
;         __builtin_amdgcn_raw_ptr_buffer_load_lds(rs_##voff, (PG8_LAS unsigned*)(lds + (bufoff) + ldsw + _i * 8192), 16, (int)(voff)[_i], so_, 0, 0); } while (0)
; #define PG8_LDA(dst, b, h) do { _Pragma("unroll") for (int m = 0; m < 4; ++m) _Pragma("unroll") for (int k = 0; k < 2; ++k) dst[m][k] = *(const PG8_LAS bf16x8*)(lds + PG8_SA(b, h) + aoff + m * 2048 + k * 1024); } while (0)
; #define PG8_LDB(dst, b, h) do { _Pragma("unroll") for (int n = 0; n < 2; ++n) _Pragma("unroll") for (int k = 0; k < 2; ++k) dst[n][k] = *(const PG8_LAS bf16x8*)(lds + PG8_SB(b, h) + boff + n * 2048 + k * 1024); } while (0)
; #define PG8_MMA(ai, bj, At, Bt) do { __builtin_amdgcn_s_setprio(1); _Pragma("unroll") for (int m = 0; m < 4; ++m) _Pragma("unroll") for (int n = 0; n < 2; ++n) _Pragma("unroll") for (int k = 0; k < 2; ++k) \
;         acc[ai][bj][m][n] = __builtin_amdgcn_mfma_f32_16x16x32_bf16(Bt[n][k], At[m][k], acc[ai][bj][m][n], 0, 0, 0); __builtin_amdgcn_s_setprio(0); } while (0)
; #define PG8_WAIT_V(n) asm volatile("s_waitcnt vmcnt(" #n ")" ::: "memory")
; #define PG8_WAIT_L(n) asm volatile("s_waitcnt lgkmcnt(" #n ")" ::: "memory")
; #define PG8_BAR __builtin_amdgcn_s_barrier()
; #define PG8_SCHED __builtin_amdgcn_sched_barrier(0)
; template <class Epi, class Sched, bool ALIGN_EPI = false, bool SP2 = false>
; __device__ __forceinline__ void gemm_phase(PG8_LAS unsigned char* lds, const Gemm g, const Sched& S, const Epi& E, int tid_in) {
;     ...
;             PG8_LDB(B0, 0, 0); PG8_LDB(B1, 0, 1); PG8_SCHED; PG8_LDA(At, 0, 0); PG8_STAGE(PG8_SA(1, 1), a1 + hstepA, voffA);
;             PG8_WAIT_V(8); PG8_WAIT_L(0); PG8_BAR; PG8_MMA(0, 0, At, B0); PG8_MMA(0, 1, At, B1); PG8_BAR; PG8_SCHED;
;             PG8_LDA(At, 0, 1); PG8_STAGE(PG8_SB(0, 0), b2, voffB); PG8_STAGE(PG8_SB(0, 1), b2 + hstepB, voffB); PG8_STAGE(PG8_SA(0, 0), a2, voffA);
;             PG8_WAIT_V(8); PG8_WAIT_L(0); PG8_BAR; PG8_MMA(1, 0, At, B0); PG8_MMA(1, 1, At, B1); PG8_BAR; PG8_SCHED;
.LBB0_1584:
	v_add_u32_e32 v133, 0x10000, v131
	ds_read_b128 v[134:137], v133
	ds_read_b128 v[138:141], v133 offset:1024
	ds_read_b128 v[142:145], v133 offset:2048
	ds_read_b128 v[146:149], v133 offset:3072
	v_add_u32_e32 v133, 0x14000, v131
	ds_read_b128 v[150:153], v133
	ds_read_b128 v[154:157], v133 offset:1024
	ds_read_b128 v[158:161], v133 offset:2048
	ds_read_b128 v[166:169], v133 offset:3072
	s_add_i32 s43, s38, s22
	s_add_i32 s42, s14, s22
	s_add_i32 s76, s12, s22
	s_addk_i32 s43, 0xff80
	s_sub_i32 s78, s43, 0x160000
	s_cmpk_eq_i32 s39, 0x54
	s_cselect_b32 s77, s16, s42
	s_mov_b32 m0, s68
	ds_read_b128 v[170:173], v132
	ds_read_b128 v[174:177], v132 offset:1024
	ds_read_b128 v[178:181], v132 offset:2048
	ds_read_b128 v[182:185], v132 offset:3072
	ds_read_b128 v[186:189], v132 offset:4096
	ds_read_b128 v[190:193], v132 offset:5120
	ds_read_b128 v[200:203], v132 offset:6144
	ds_read_b128 v[206:209], v132 offset:7168
	s_mov_b32 m0, s63
	s_nop 0
	buffer_load_dwordx4 v130, s[4:7], s78 offen lds
	s_mov_b32 m0, s68
	s_nop 0
	buffer_load_dwordx4 v0, s[4:7], s43 offen lds
	s_mov_b32 m0, s69
	s_nop 0
	buffer_load_dwordx4 v130, s[4:7], s43 offen lds
	s_waitcnt vmcnt(8)
	s_waitcnt lgkmcnt(0)
	s_barrier
	s_setprio 1
	s_waitcnt lgkmcnt(0)
	v_mfma_f32_16x16x32_bf16 v[22:25], v[134:137], v[170:173], v[22:25]
	v_mfma_f32_16x16x32_bf16 v[14:17], v[142:145], v[170:173], v[14:17]
	v_mfma_f32_16x16x32_bf16 v[74:77], v[134:137], v[178:181], v[74:77]
	v_mfma_f32_16x16x32_bf16 v[54:57], v[142:145], v[178:181], v[54:57]
	v_mfma_f32_16x16x32_bf16 v[106:109], v[134:137], v[186:189], v[106:109]
	v_mfma_f32_16x16x32_bf16 v[102:105], v[142:145], v[186:189], v[102:105]
	v_mfma_f32_16x16x32_bf16 v[122:125], v[134:137], v[200:203], v[122:125]
	v_mfma_f32_16x16x32_bf16 v[118:121], v[142:145], v[200:203], v[118:121]
	v_mfma_f32_16x16x32_bf16 v[22:25], v[138:141], v[174:177], v[22:25]
	v_mfma_f32_16x16x32_bf16 v[14:17], v[146:149], v[174:177], v[14:17]
	v_mfma_f32_16x16x32_bf16 v[74:77], v[138:141], v[182:185], v[74:77]
	v_mfma_f32_16x16x32_bf16 v[54:57], v[146:149], v[182:185], v[54:57]
	v_mfma_f32_16x16x32_bf16 v[106:109], v[138:141], v[190:193], v[106:109]
	v_mfma_f32_16x16x32_bf16 v[102:105], v[146:149], v[190:193], v[102:105]
	v_mfma_f32_16x16x32_bf16 v[122:125], v[138:141], v[206:209], v[122:125]
	v_mfma_f32_16x16x32_bf16 v[118:121], v[146:149], v[206:209], v[118:121]
	s_setprio 0
	s_setprio 1
	v_mfma_f32_16x16x32_bf16 v[6:9], v[150:153], v[170:173], v[6:9]
	v_mfma_f32_16x16x32_bf16 v[18:21], v[158:161], v[170:173], v[18:21]
	v_mfma_f32_16x16x32_bf16 v[50:53], v[150:153], v[178:181], v[50:53]
	v_mfma_f32_16x16x32_bf16 v[78:81], v[158:161], v[178:181], v[78:81]
	v_mfma_f32_16x16x32_bf16 v[98:101], v[150:153], v[186:189], v[98:101]
	v_mfma_f32_16x16x32_bf16 v[110:113], v[158:161], v[186:189], v[110:113]
	v_mfma_f32_16x16x32_bf16 v[114:117], v[150:153], v[200:203], v[114:117]
	v_mfma_f32_16x16x32_bf16 v[126:129], v[158:161], v[200:203], v[126:129]
	v_mfma_f32_16x16x32_bf16 v[6:9], v[154:157], v[174:177], v[6:9]
	v_mfma_f32_16x16x32_bf16 v[18:21], v[166:169], v[174:177], v[18:21]
	v_mfma_f32_16x16x32_bf16 v[50:53], v[154:157], v[182:185], v[50:53]
	v_mfma_f32_16x16x32_bf16 v[78:81], v[166:169], v[182:185], v[78:81]
	v_mfma_f32_16x16x32_bf16 v[98:101], v[154:157], v[190:193], v[98:101]
	v_mfma_f32_16x16x32_bf16 v[110:113], v[166:169], v[190:193], v[110:113]
	v_mfma_f32_16x16x32_bf16 v[114:117], v[154:157], v[206:209], v[114:117]
	v_mfma_f32_16x16x32_bf16 v[126:129], v[166:169], v[206:209], v[126:129]
	s_setprio 0
	s_barrier
	s_cselect_b32 s76, s20, s76
	s_mov_b32 m0, s26
	s_mov_b32 s42, s6
	s_mov_b32 s43, s7
	s_sub_i32 s76, s76, s40
	ds_read_b128 v[170:173], v132 offset:16384
	ds_read_b128 v[174:177], v132 offset:17408
	ds_read_b128 v[178:181], v132 offset:18432
	ds_read_b128 v[182:185], v132 offset:19456
	ds_read_b128 v[186:189], v132 offset:20480
	ds_read_b128 v[190:193], v132 offset:21504
	ds_read_b128 v[200:203], v132 offset:22528
	ds_read_b128 v[206:209], v132 offset:23552
	buffer_load_dwordx4 v0, s[40:43], s76 offen lds
	s_mov_b32 m0, s44
	s_add_i32 s78, s76, 0x160000
	buffer_load_dwordx4 v130, s[40:43], s76 offen lds
	s_mov_b32 m0, s45
	s_sub_i32 s77, s77, s4
	buffer_load_dwordx4 v0, s[40:43], s78 offen lds
	s_mov_b32 m0, s46
	s_nop 0
	buffer_load_dwordx4 v130, s[40:43], s78 offen lds
	s_mov_b32 m0, s19
	s_nop 0
	buffer_load_dwordx4 v0, s[4:7], s77 offen lds
	s_waitcnt vmcnt(7)
	s_waitcnt lgkmcnt(0)
	s_barrier
	s_setprio 1
	s_waitcnt lgkmcnt(0)
	v_mfma_f32_16x16x32_bf16 v[62:65], v[134:137], v[170:173], v[62:65]
	v_mfma_f32_16x16x32_bf16 v[46:49], v[142:145], v[170:173], v[46:49]
	v_mfma_f32_16x16x32_bf16 v[82:85], v[134:137], v[178:181], v[82:85]
	v_mfma_f32_16x16x32_bf16 v[70:73], v[142:145], v[178:181], v[70:73]
	v_mfma_f32_16x16x32_bf16 v[94:97], v[134:137], v[186:189], v[94:97]
	v_mfma_f32_16x16x32_bf16 v[90:93], v[142:145], v[186:189], v[90:93]
	v_mfma_f32_16x16x32_bf16 v[38:41], v[134:137], v[200:203], v[38:41]
	v_mfma_f32_16x16x32_bf16 v[26:29], v[142:145], v[200:203], v[26:29]
	v_mfma_f32_16x16x32_bf16 v[62:65], v[138:141], v[174:177], v[62:65]
	v_mfma_f32_16x16x32_bf16 v[46:49], v[146:149], v[174:177], v[46:49]
	v_mfma_f32_16x16x32_bf16 v[82:85], v[138:141], v[182:185], v[82:85]
	v_mfma_f32_16x16x32_bf16 v[70:73], v[146:149], v[182:185], v[70:73]
	v_mfma_f32_16x16x32_bf16 v[94:97], v[138:141], v[190:193], v[94:97]
	v_mfma_f32_16x16x32_bf16 v[90:93], v[146:149], v[190:193], v[90:93]
	v_mfma_f32_16x16x32_bf16 v[38:41], v[138:141], v[206:209], v[38:41]
	v_mfma_f32_16x16x32_bf16 v[26:29], v[146:149], v[206:209], v[26:29]
	s_setprio 0
	s_setprio 1
	v_mfma_f32_16x16x32_bf16 v[42:45], v[150:153], v[170:173], v[42:45]
	v_mfma_f32_16x16x32_bf16 v[30:33], v[158:161], v[170:173], v[30:33]
	v_mfma_f32_16x16x32_bf16 v[66:69], v[150:153], v[178:181], v[66:69]
	v_mfma_f32_16x16x32_bf16 v[86:89], v[158:161], v[178:181], v[86:89]
	v_mfma_f32_16x16x32_bf16 v[58:61], v[150:153], v[186:189], v[58:61]
	v_mfma_f32_16x16x32_bf16 v[34:37], v[158:161], v[186:189], v[34:37]
	v_mfma_f32_16x16x32_bf16 v[10:13], v[150:153], v[200:203], v[10:13]
	v_mfma_f32_16x16x32_bf16 v[2:5], v[158:161], v[200:203], v[2:5]
	v_mfma_f32_16x16x32_bf16 v[42:45], v[154:157], v[174:177], v[42:45]
	v_mfma_f32_16x16x32_bf16 v[30:33], v[166:169], v[174:177], v[30:33]
	v_mfma_f32_16x16x32_bf16 v[66:69], v[154:157], v[182:185], v[66:69]
	v_mfma_f32_16x16x32_bf16 v[86:89], v[166:169], v[182:185], v[86:89]
	v_mfma_f32_16x16x32_bf16 v[58:61], v[154:157], v[190:193], v[58:61]
	v_mfma_f32_16x16x32_bf16 v[34:37], v[166:169], v[190:193], v[34:37]
	v_mfma_f32_16x16x32_bf16 v[10:13], v[154:157], v[206:209], v[10:13]
	v_mfma_f32_16x16x32_bf16 v[2:5], v[166:169], v[206:209], v[2:5]
	s_setprio 0
	s_barrier
; #define PG8_STAGE(bufoff, gbase, voff) do { const int so_ = (int)(unsigned)((const char*)(gbase) - base_##voff); _Pragma("unroll") for (int _i = 0; _i < 2; ++_i) \
;         __builtin_amdgcn_raw_ptr_buffer_load_lds(rs_##voff, (PG8_LAS unsigned*)(lds + (bufoff) + ldsw + _i * 8192), 16, (int)(voff)[_i], so_, 0, 0); } while (0)
; #define PG8_LDA(dst, b, h) do { _Pragma("unroll") for (int m = 0; m < 4; ++m) _Pragma("unroll") for (int k = 0; k < 2; ++k) dst[m][k] = *(const PG8_LAS bf16x8*)(lds + PG8_SA(b, h) + aoff + m * 2048 + k * 1024); } while (0)
; #define PG8_LDB(dst, b, h) do { _Pragma("unroll") for (int n = 0; n < 2; ++n) _Pragma("unroll") for (int k = 0; k < 2; ++k) dst[n][k] = *(const PG8_LAS bf16x8*)(lds + PG8_SB(b, h) + boff + n * 2048 + k * 1024); } while (0)
; #define PG8_MMA(ai, bj, At, Bt) do { __builtin_amdgcn_s_setprio(1); _Pragma("unroll") for (int m = 0; m < 4; ++m) _Pragma("unroll") for (int n = 0; n < 2; ++n) _Pragma("unroll") for (int k = 0; k < 2; ++k) \
;         acc[ai][bj][m][n] = __builtin_amdgcn_mfma_f32_16x16x32_bf16(Bt[n][k], At[m][k], acc[ai][bj][m][n], 0, 0, 0); __builtin_amdgcn_s_setprio(0); } while (0)
; #define PG8_WAIT_V(n) asm volatile("s_waitcnt vmcnt(" #n ")" ::: "memory")
; #define PG8_WAIT_L(n) asm volatile("s_waitcnt lgkmcnt(" #n ")" ::: "memory")
; #define PG8_BAR __builtin_amdgcn_s_barrier()
; #define PG8_SCHED __builtin_amdgcn_sched_barrier(0)
; template <class Epi, class Sched, bool ALIGN_EPI = false, bool SP2 = false>
; __device__ __forceinline__ void gemm_phase(PG8_LAS unsigned char* lds, const Gemm g, const Sched& S, const Epi& E, int tid_in) {
;     ...
;             PG8_LDB(B0, 1, 0); PG8_LDB(B1, 1, 1); PG8_SCHED; PG8_LDA(At, 1, 0); PG8_STAGE(PG8_SA(0, 1), a2 + hstepA, voffA);
;             PG8_WAIT_V(8); PG8_WAIT_L(0); PG8_BAR; PG8_MMA(0, 0, At, B0); PG8_MMA(0, 1, At, B1); PG8_BAR; PG8_SCHED;
;             PG8_LDA(At, 1, 1); PG8_STAGE(PG8_SB(1, 0), b3, voffB); PG8_STAGE(PG8_SB(1, 1), b3 + hstepB, voffB); PG8_STAGE(PG8_SA(1, 0), a3, voffA);
;             PG8_WAIT_V(8); PG8_WAIT_L(0); PG8_BAR; PG8_MMA(1, 0, At, B0); PG8_MMA(1, 1, At, B1); PG8_BAR; PG8_SCHED;
	v_add_u32_e32 v133, 0x18000, v131
	ds_read_b128 v[134:137], v133
	ds_read_b128 v[138:141], v133 offset:1024
	ds_read_b128 v[142:145], v133 offset:2048
	ds_read_b128 v[146:149], v133 offset:3072
	v_add_u32_e32 v133, 0x1c000, v131
	ds_read_b128 v[150:153], v133
	ds_read_b128 v[154:157], v133 offset:1024
	ds_read_b128 v[158:161], v133 offset:2048
	ds_read_b128 v[166:169], v133 offset:3072
	s_add_i32 s78, s77, 0x160000
	s_mov_b32 m0, s48
	ds_read_b128 v[170:173], v132 offset:32768
	ds_read_b128 v[174:177], v132 offset:33792
	ds_read_b128 v[178:181], v132 offset:34816
	ds_read_b128 v[182:185], v132 offset:35840
	ds_read_b128 v[186:189], v132 offset:36864
	ds_read_b128 v[190:193], v132 offset:37888
	ds_read_b128 v[200:203], v132 offset:38912
	ds_read_b128 v[206:209], v132 offset:39936
	s_mov_b32 m0, s47
	s_nop 0
	buffer_load_dwordx4 v130, s[4:7], s77 offen lds
	s_mov_b32 m0, s48
	s_nop 0
	buffer_load_dwordx4 v0, s[4:7], s78 offen lds
	s_mov_b32 m0, s49
	s_nop 0
	buffer_load_dwordx4 v130, s[4:7], s78 offen lds
	s_waitcnt vmcnt(8)
	s_waitcnt lgkmcnt(0)
	s_barrier
	s_setprio 1
	s_waitcnt lgkmcnt(0)
	v_mfma_f32_16x16x32_bf16 v[22:25], v[134:137], v[170:173], v[22:25]
	v_mfma_f32_16x16x32_bf16 v[14:17], v[142:145], v[170:173], v[14:17]
	v_mfma_f32_16x16x32_bf16 v[74:77], v[134:137], v[178:181], v[74:77]
	v_mfma_f32_16x16x32_bf16 v[54:57], v[142:145], v[178:181], v[54:57]
	v_mfma_f32_16x16x32_bf16 v[106:109], v[134:137], v[186:189], v[106:109]
	v_mfma_f32_16x16x32_bf16 v[102:105], v[142:145], v[186:189], v[102:105]
	v_mfma_f32_16x16x32_bf16 v[122:125], v[134:137], v[200:203], v[122:125]
	v_mfma_f32_16x16x32_bf16 v[118:121], v[142:145], v[200:203], v[118:121]
	v_mfma_f32_16x16x32_bf16 v[22:25], v[138:141], v[174:177], v[22:25]
	v_mfma_f32_16x16x32_bf16 v[14:17], v[146:149], v[174:177], v[14:17]
	v_mfma_f32_16x16x32_bf16 v[74:77], v[138:141], v[182:185], v[74:77]
	v_mfma_f32_16x16x32_bf16 v[54:57], v[146:149], v[182:185], v[54:57]
	v_mfma_f32_16x16x32_bf16 v[106:109], v[138:141], v[190:193], v[106:109]
	v_mfma_f32_16x16x32_bf16 v[102:105], v[146:149], v[190:193], v[102:105]
	v_mfma_f32_16x16x32_bf16 v[122:125], v[138:141], v[206:209], v[122:125]
	v_mfma_f32_16x16x32_bf16 v[118:121], v[146:149], v[206:209], v[118:121]
	s_setprio 0
	s_setprio 1
	v_mfma_f32_16x16x32_bf16 v[6:9], v[150:153], v[170:173], v[6:9]
	v_mfma_f32_16x16x32_bf16 v[18:21], v[158:161], v[170:173], v[18:21]
	v_mfma_f32_16x16x32_bf16 v[50:53], v[150:153], v[178:181], v[50:53]
	v_mfma_f32_16x16x32_bf16 v[78:81], v[158:161], v[178:181], v[78:81]
	v_mfma_f32_16x16x32_bf16 v[98:101], v[150:153], v[186:189], v[98:101]
	v_mfma_f32_16x16x32_bf16 v[110:113], v[158:161], v[186:189], v[110:113]
	v_mfma_f32_16x16x32_bf16 v[114:117], v[150:153], v[200:203], v[114:117]
	v_mfma_f32_16x16x32_bf16 v[126:129], v[158:161], v[200:203], v[126:129]
	v_mfma_f32_16x16x32_bf16 v[6:9], v[154:157], v[174:177], v[6:9]
	v_mfma_f32_16x16x32_bf16 v[18:21], v[166:169], v[174:177], v[18:21]
	v_mfma_f32_16x16x32_bf16 v[50:53], v[154:157], v[182:185], v[50:53]
	v_mfma_f32_16x16x32_bf16 v[78:81], v[166:169], v[182:185], v[78:81]
	v_mfma_f32_16x16x32_bf16 v[98:101], v[154:157], v[190:193], v[98:101]
	v_mfma_f32_16x16x32_bf16 v[110:113], v[166:169], v[190:193], v[110:113]
	v_mfma_f32_16x16x32_bf16 v[114:117], v[154:157], v[206:209], v[114:117]
	v_mfma_f32_16x16x32_bf16 v[126:129], v[166:169], v[206:209], v[126:129]
	s_setprio 0
	s_barrier
	s_mov_b32 m0, s60
	s_add_i32 s78, s76, 0x80
	ds_read_b128 v[170:173], v132 offset:49152
	ds_read_b128 v[174:177], v132 offset:50176
	ds_read_b128 v[178:181], v132 offset:51200
	ds_read_b128 v[182:185], v132 offset:52224
	ds_read_b128 v[186:189], v132 offset:53248
	ds_read_b128 v[190:193], v132 offset:54272
	ds_read_b128 v[200:203], v132 offset:55296
	ds_read_b128 v[206:209], v132 offset:56320
	buffer_load_dwordx4 v0, s[40:43], s78 offen lds
	s_mov_b32 m0, s61
	s_add_i32 s76, s76, 0x160080
	buffer_load_dwordx4 v130, s[40:43], s78 offen lds
	s_mov_b32 m0, s66
	s_addk_i32 s77, 0x80
	buffer_load_dwordx4 v0, s[40:43], s76 offen lds
	s_mov_b32 m0, s67
	s_nop 0
	buffer_load_dwordx4 v130, s[40:43], s76 offen lds
	s_mov_b32 m0, s62
	s_nop 0
	buffer_load_dwordx4 v0, s[4:7], s77 offen lds
	s_waitcnt vmcnt(7)
	s_waitcnt lgkmcnt(0)
	s_barrier
; #define PG8_MMA(ai, bj, At, Bt) do { __builtin_amdgcn_s_setprio(1); _Pragma("unroll") for (int m = 0; m < 4; ++m) _Pragma("unroll") for (int n = 0; n < 2; ++n) _Pragma("unroll") for (int k = 0; k < 2; ++k) \
;         acc[ai][bj][m][n] = __builtin_amdgcn_mfma_f32_16x16x32_bf16(Bt[n][k], At[m][k], acc[ai][bj][m][n], 0, 0, 0); __builtin_amdgcn_s_setprio(0); } while (0)
; #define PG8_WAIT_V(n) asm volatile("s_waitcnt vmcnt(" #n ")" ::: "memory")
; #define PG8_WAIT_L(n) asm volatile("s_waitcnt lgkmcnt(" #n ")" ::: "memory")
; #define PG8_BAR __builtin_amdgcn_s_barrier()
; #define PG8_SCHED __builtin_amdgcn_sched_barrier(0)
; template <class Epi, class Sched, bool ALIGN_EPI = false, bool SP2 = false>
; __device__ __forceinline__ void gemm_phase(PG8_LAS unsigned char* lds, const Gemm g, const Sched& S, const Epi& E, int tid_in) {
;     ...
;             PG8_WAIT_V(8); PG8_WAIT_L(0); PG8_BAR; PG8_MMA(1, 0, At, B0); PG8_MMA(1, 1, At, B1); PG8_BAR; PG8_SCHED;
;     ...
;         if (zero_acc) {
; #pragma unroll
;         for (int a = 0; a < 2; ++a)
; #pragma unroll
;             for (int b = 0; b < 2; ++b)
; #pragma unroll
;                 for (int m = 0; m < 4; ++m)
; #pragma unroll
;                     for (int n = 0; n < 2; ++n) acc[a][b][m][n] = (f32x4){0.f, 0.f, 0.f, 0.f};
;         }
	s_setprio 1
	s_waitcnt lgkmcnt(0)
	v_mfma_f32_16x16x32_bf16 v[62:65], v[134:137], v[170:173], v[62:65]
	v_mfma_f32_16x16x32_bf16 v[46:49], v[142:145], v[170:173], v[46:49]
	v_mfma_f32_16x16x32_bf16 v[82:85], v[134:137], v[178:181], v[82:85]
	v_mfma_f32_16x16x32_bf16 v[70:73], v[142:145], v[178:181], v[70:73]
	v_mfma_f32_16x16x32_bf16 v[94:97], v[134:137], v[186:189], v[94:97]
	v_mfma_f32_16x16x32_bf16 v[90:93], v[142:145], v[186:189], v[90:93]
	v_mfma_f32_16x16x32_bf16 v[38:41], v[134:137], v[200:203], v[38:41]
	v_mfma_f32_16x16x32_bf16 v[26:29], v[142:145], v[200:203], v[26:29]
	v_mfma_f32_16x16x32_bf16 v[62:65], v[138:141], v[174:177], v[62:65]
	v_mfma_f32_16x16x32_bf16 v[46:49], v[146:149], v[174:177], v[46:49]
	v_mfma_f32_16x16x32_bf16 v[82:85], v[138:141], v[182:185], v[82:85]
	v_mfma_f32_16x16x32_bf16 v[70:73], v[146:149], v[182:185], v[70:73]
	v_mfma_f32_16x16x32_bf16 v[94:97], v[138:141], v[190:193], v[94:97]
	v_mfma_f32_16x16x32_bf16 v[90:93], v[146:149], v[190:193], v[90:93]
	v_mfma_f32_16x16x32_bf16 v[38:41], v[138:141], v[206:209], v[38:41]
	v_mfma_f32_16x16x32_bf16 v[26:29], v[146:149], v[206:209], v[26:29]
	s_setprio 0
	s_setprio 1
	v_mfma_f32_16x16x32_bf16 v[42:45], v[150:153], v[170:173], v[42:45]
	v_mfma_f32_16x16x32_bf16 v[30:33], v[158:161], v[170:173], v[30:33]
	v_mfma_f32_16x16x32_bf16 v[66:69], v[150:153], v[178:181], v[66:69]
	v_mfma_f32_16x16x32_bf16 v[86:89], v[158:161], v[178:181], v[86:89]
	v_mfma_f32_16x16x32_bf16 v[58:61], v[150:153], v[186:189], v[58:61]
	v_mfma_f32_16x16x32_bf16 v[34:37], v[158:161], v[186:189], v[34:37]
	v_mfma_f32_16x16x32_bf16 v[10:13], v[150:153], v[200:203], v[10:13]
	v_mfma_f32_16x16x32_bf16 v[2:5], v[158:161], v[200:203], v[2:5]
	v_mfma_f32_16x16x32_bf16 v[42:45], v[154:157], v[174:177], v[42:45]
	v_mfma_f32_16x16x32_bf16 v[30:33], v[166:169], v[174:177], v[30:33]
	v_mfma_f32_16x16x32_bf16 v[66:69], v[154:157], v[182:185], v[66:69]
	v_mfma_f32_16x16x32_bf16 v[86:89], v[166:169], v[182:185], v[86:89]
	v_mfma_f32_16x16x32_bf16 v[58:61], v[154:157], v[190:193], v[58:61]
	v_mfma_f32_16x16x32_bf16 v[34:37], v[166:169], v[190:193], v[34:37]
	v_mfma_f32_16x16x32_bf16 v[10:13], v[154:157], v[206:209], v[10:13]
	v_mfma_f32_16x16x32_bf16 v[2:5], v[166:169], v[206:209], v[2:5]
	s_setprio 0
	s_barrier
	s_add_i32 s39, s39, 2
	s_add_u32 s22, s22, 0x100
	s_addc_u32 s23, s23, 0
	s_cmpk_gt_u32 s39, 0x55
	s_cbranch_scc0 .LBB0_1584
	s_and_b64 vcc, exec, s[36:37]
	s_cbranch_vccnz .LBB0_1572
	v_mov_b32_e32 v2, 0
	s_mov_b32 s10, s73
	s_mov_b32 s25, s74
	s_mov_b64 s[12:13], s[20:21]
	s_mov_b64 s[14:15], s[16:17]
	s_mov_b32 s72, s75
	v_mov_b32_e32 v3, v2
	v_mov_b32_e32 v4, v2
	v_mov_b32_e32 v5, v2
	v_mov_b32_e32 v10, v2
	v_mov_b32_e32 v11, v2
	v_mov_b32_e32 v12, v2
	v_mov_b32_e32 v13, v2
	v_mov_b32_e32 v34, v2
	v_mov_b32_e32 v35, v2
	v_mov_b32_e32 v36, v2
	v_mov_b32_e32 v37, v2
	v_mov_b32_e32 v58, v2
	v_mov_b32_e32 v59, v2
	v_mov_b32_e32 v60, v2
	v_mov_b32_e32 v61, v2
	v_mov_b32_e32 v86, v2
	v_mov_b32_e32 v87, v2
	v_mov_b32_e32 v88, v2
	v_mov_b32_e32 v89, v2
	v_mov_b32_e32 v66, v2
	v_mov_b32_e32 v67, v2
	v_mov_b32_e32 v68, v2
	v_mov_b32_e32 v69, v2
	v_mov_b32_e32 v30, v2
	v_mov_b32_e32 v31, v2
	v_mov_b32_e32 v32, v2
	v_mov_b32_e32 v33, v2
	v_mov_b32_e32 v42, v2
	v_mov_b32_e32 v43, v2
	v_mov_b32_e32 v44, v2
	v_mov_b32_e32 v45, v2
	v_mov_b32_e32 v26, v2
	v_mov_b32_e32 v27, v2
	v_mov_b32_e32 v28, v2
	v_mov_b32_e32 v29, v2
	v_mov_b32_e32 v38, v2
	v_mov_b32_e32 v39, v2
	v_mov_b32_e32 v40, v2
	v_mov_b32_e32 v41, v2
	v_mov_b32_e32 v90, v2
	v_mov_b32_e32 v91, v2
	v_mov_b32_e32 v92, v2
	v_mov_b32_e32 v93, v2
	v_mov_b32_e32 v94, v2
	v_mov_b32_e32 v95, v2
	v_mov_b32_e32 v96, v2
	v_mov_b32_e32 v97, v2
	v_mov_b32_e32 v70, v2
	v_mov_b32_e32 v71, v2
	v_mov_b32_e32 v72, v2
	v_mov_b32_e32 v73, v2
	v_mov_b32_e32 v82, v2
	v_mov_b32_e32 v83, v2
	v_mov_b32_e32 v84, v2
	v_mov_b32_e32 v85, v2
	v_mov_b32_e32 v46, v2
	v_mov_b32_e32 v47, v2
	v_mov_b32_e32 v48, v2
	v_mov_b32_e32 v49, v2
	v_mov_b32_e32 v62, v2
	v_mov_b32_e32 v63, v2
	v_mov_b32_e32 v64, v2
	v_mov_b32_e32 v65, v2
	v_mov_b32_e32 v126, v2
	v_mov_b32_e32 v127, v2
	v_mov_b32_e32 v128, v2
	v_mov_b32_e32 v129, v2
	v_mov_b32_e32 v114, v2
	v_mov_b32_e32 v115, v2
	v_mov_b32_e32 v116, v2
	v_mov_b32_e32 v117, v2
	v_mov_b32_e32 v110, v2
	v_mov_b32_e32 v111, v2
	v_mov_b32_e32 v112, v2
	v_mov_b32_e32 v113, v2
	v_mov_b32_e32 v98, v2
	v_mov_b32_e32 v99, v2
	v_mov_b32_e32 v100, v2
	v_mov_b32_e32 v101, v2
	v_mov_b32_e32 v78, v2
	v_mov_b32_e32 v79, v2
	v_mov_b32_e32 v80, v2
	v_mov_b32_e32 v81, v2
	v_mov_b32_e32 v50, v2
	v_mov_b32_e32 v51, v2
	v_mov_b32_e32 v52, v2
	v_mov_b32_e32 v53, v2
	v_mov_b32_e32 v18, v2
	v_mov_b32_e32 v19, v2
	v_mov_b32_e32 v20, v2
	v_mov_b32_e32 v21, v2
	v_mov_b32_e32 v6, v2
	v_mov_b32_e32 v7, v2
	v_mov_b32_e32 v8, v2
	v_mov_b32_e32 v9, v2
	v_mov_b32_e32 v118, v2
	v_mov_b32_e32 v119, v2
	v_mov_b32_e32 v120, v2
	v_mov_b32_e32 v121, v2
	v_mov_b32_e32 v122, v2
	v_mov_b32_e32 v123, v2
	v_mov_b32_e32 v124, v2
	v_mov_b32_e32 v125, v2
	v_mov_b32_e32 v102, v2
	v_mov_b32_e32 v103, v2
	v_mov_b32_e32 v104, v2
	v_mov_b32_e32 v105, v2
	v_mov_b32_e32 v106, v2
	v_mov_b32_e32 v107, v2
	v_mov_b32_e32 v108, v2
	v_mov_b32_e32 v109, v2
	v_mov_b32_e32 v54, v2
	v_mov_b32_e32 v55, v2
	v_mov_b32_e32 v56, v2
	v_mov_b32_e32 v57, v2
	v_mov_b32_e32 v74, v2
	v_mov_b32_e32 v75, v2
	v_mov_b32_e32 v76, v2
	v_mov_b32_e32 v77, v2
	v_mov_b32_e32 v14, v2
	v_mov_b32_e32 v15, v2
	v_mov_b32_e32 v16, v2
	v_mov_b32_e32 v17, v2
	v_mov_b32_e32 v22, v2
	v_mov_b32_e32 v23, v2
	v_mov_b32_e32 v24, v2
	v_mov_b32_e32 v25, v2
	s_branch .LBB0_1572
